# speedup vs baseline: 1.0128x; 1.0128x over previous
; #define RK ((bfraw*)(kargs()->ws + O_RK))
; #define RVT ((bfraw*)(kargs()->ws + O_RVT))
; #define ST ((bfraw*)(kargs()->ws + O_ST))
; #define LGT ((float*)(kargs()->ws + O_LGT))
; __global__ void __launch_bounds__(512) mega(Params p) {
;     ...
;         for (int bi = bid; bi < 128 * 8; bi += nb) {
;           int tz = tid; asm volatile("" : "+v"(tz));
;           const int w = __builtin_amdgcn_readfirstlane(tz >> 6), lz = tz & 63, fr = tz & 15, fq = (tz >> 4) & 3;
;           const int head = bi & 7, chunk = bi >> 3;
;           const float lgf = LGT[l * 16 + head], lgb = LGT[l * 16 + 8 + head];
;           const long tok0 = (long)chunk * 128;
;           __syncthreads();
;           { const bfraw* kb = RK + tok0 * 1024 + head * 128; const bfraw* vb = RVT + ((long)(chunk * 8 + head) * 128) * 128;
;             const bfraw* sfb = ST + ((long)((chunk * 8 + head) * 2)) * 16384;
;             const int wz = w;
; #pragma unroll
;             for (int g = 0; g < 16; ++g) { const int blk = g * 8 + wz, row = (blk & 31) * 4 + (lz >> 4), c = (lz ^ row) & 15;
;               const bfraw* sp = (g < 4) ? kb + (long)row * 1024 + c * 8 : (g < 8) ? vb + row * 128 + c * 8 : sfb + (g < 12 ? 0 : 16384) + row * 128 + c * 8;
;               __builtin_amdgcn_global_load_lds((const unsigned*)sp, (unsigned*)(shm + blk * 1024), 16, 0, 0); } }
.LBB0_2481:
	v_mov_b32_e32 v116, v114
	s_and_b32 s17, s16, 7
	v_readfirstlane_b32 s2, v116
	s_ashr_i32 s18, s2, 6
	s_mov_b64 s[2:3], s[0:1]
	s_load_dwordx2 s[4:5], s[2:3], 0xe8
	s_or_b32 s12, s17, s10
	s_ashr_i32 s2, s16, 3
	s_lshl_b64 s[14:15], s[12:13], 2
	v_bfe_u32 v68, v116, 4, 2
	s_waitcnt lgkmcnt(0)
	s_add_u32 s4, s4, s14
	s_addc_u32 s5, s5, s15
	global_load_dword v117, v252, s[4:5]
	s_mov_b64 s[4:5], s[0:1]
	s_load_dwordx2 s[4:5], s[4:5], 0xe8
	v_and_b32_e32 v115, 15, v116
	v_lshrrev_b32_e32 v119, 4, v116
	v_lshlrev_b32_e32 v120, 8, v115
	v_bitop3_b32 v8, v68, v115, 4 bitop3:0x36
	s_waitcnt lgkmcnt(0)
	s_add_u32 s4, s4, s14
	s_addc_u32 s5, s5, s15
	global_load_dword v118, v252, s[4:5] offset:32
	s_mov_b64 s[4:5], s[0:1]
	s_waitcnt vmcnt(63) expcnt(7) lgkmcnt(15)
	s_barrier
	s_load_dwordx2 s[4:5], s[4:5], 0xe8
	s_ashr_i32 s3, s2, 31
	s_lshl_b64 s[14:15], s[2:3], 18
	v_bitop3_b32 v16, v68, v115, 8 bitop3:0x36
	v_bitop3_b32 v26, v68, v115, 12 bitop3:0x36
	s_waitcnt lgkmcnt(0)
	s_add_u32 s4, s4, s14
	s_addc_u32 s5, s5, s15
	s_lshl_b32 s12, s17, 8
	s_add_u32 s7, s4, s12
	s_addc_u32 s19, s5, 0
	s_mov_b64 s[4:5], s[0:1]
	s_load_dwordx2 s[14:15], s[4:5], 0xe8
	s_mov_b64 s[4:5], s[0:1]
	s_load_dwordx2 s[4:5], s[4:5], 0xe8
	s_add_u32 s20, s7, 0x13720000
	s_addc_u32 s21, s19, 0
	s_ashr_i32 s7, s6, 31
	s_lshl_b64 s[22:23], s[6:7], 15
	s_waitcnt lgkmcnt(0)
	s_add_u32 s7, s4, s22
	s_addc_u32 s19, s5, s23
	s_add_u32 s4, s7, 0x30720000
	s_addc_u32 s5, s19, 0
	s_lshl_b32 s22, s18, 2
	s_and_b32 s22, s22, 0x7c
	v_or_b32_e32 v0, s22, v68
	v_bitop3_b32 v2, s22, v116, v68 bitop3:0x36
	v_lshlrev_b32_e32 v176, 11, v0
	v_lshlrev_b32_e32 v2, 4, v2
	s_add_i32 s22, s18, 8
	v_lshl_add_u64 v[0:1], s[20:21], 0, v[176:177]
	v_and_b32_e32 v176, 0xf0, v2
	s_lshl_b32 s23, s22, 2
	v_lshl_add_u64 v[0:1], v[0:1], 0, v[176:177]
	s_lshl_b32 m0, s18, 10
	s_and_b32 s23, s23, 0x7c
	global_load_lds_dwordx4 v[0:1], off
	v_or_b32_e32 v0, s23, v68
	v_bitop3_b32 v2, s23, v116, v68 bitop3:0x36
	v_lshlrev_b32_e32 v176, 11, v0
	v_lshlrev_b32_e32 v2, 4, v2
	s_lshl_b32 m0, s22, 10
	s_add_i32 s22, s18, 16
	v_lshl_add_u64 v[0:1], s[20:21], 0, v[176:177]
	v_and_b32_e32 v176, 0xf0, v2
	s_lshl_b32 s23, s22, 2
	v_lshl_add_u64 v[0:1], v[0:1], 0, v[176:177]
	s_and_b32 s23, s23, 0x7c
	global_load_lds_dwordx4 v[0:1], off
	v_or_b32_e32 v0, s23, v68
	v_bitop3_b32 v2, s23, v116, v68 bitop3:0x36
	v_lshlrev_b32_e32 v176, 11, v0
	v_lshlrev_b32_e32 v2, 4, v2
	s_lshl_b32 m0, s22, 10
	s_add_i32 s22, s18, 24
	v_lshl_add_u64 v[0:1], s[20:21], 0, v[176:177]
	v_and_b32_e32 v176, 0xf0, v2
	s_lshl_b32 s23, s22, 2
	v_lshl_add_u64 v[0:1], v[0:1], 0, v[176:177]
	s_and_b32 s23, s23, 0x7c
	global_load_lds_dwordx4 v[0:1], off
	v_or_b32_e32 v0, s23, v68
	v_bitop3_b32 v2, s23, v116, v68 bitop3:0x36
	v_lshlrev_b32_e32 v176, 11, v0
	v_lshlrev_b32_e32 v2, 4, v2
	v_lshl_add_u64 v[0:1], s[20:21], 0, v[176:177]
	v_and_b32_e32 v176, 0xf0, v2
	v_lshl_add_u64 v[0:1], v[0:1], 0, v[176:177]
	s_lshl_b32 m0, s22, 10
	s_add_i32 s20, s18, 32
	global_load_lds_dwordx4 v[0:1], off
	v_lshl_or_b32 v0, s20, 2, v68
	s_and_b32 s21, s20, 31
	v_lshlrev_b32_e32 v2, 8, v68
	v_bitop3_b32 v0, v0, 15, v116 bitop3:0x48
	v_lshl_or_b32 v1, s21, 10, v2
	v_lshl_or_b32 v176, v0, 4, v1
	v_lshl_add_u64 v[0:1], s[14:15], 0, v[176:177]
	v_lshl_add_u64 v[0:1], v[0:1], 0, s[8:9]
	s_lshl_b32 m0, s20, 10
	s_add_i32 s20, s18, 40
	global_load_lds_dwordx4 v[0:1], off
	v_lshl_or_b32 v0, s20, 2, v68
	s_and_b32 s21, s20, 31
	v_bitop3_b32 v0, v0, 15, v116 bitop3:0x48
	v_lshl_or_b32 v1, s21, 10, v2
	v_lshl_or_b32 v176, v0, 4, v1
	v_lshl_add_u64 v[0:1], s[14:15], 0, v[176:177]
	v_lshl_add_u64 v[0:1], v[0:1], 0, s[8:9]
	s_lshl_b32 m0, s20, 10
	s_add_i32 s20, s18, 48
	global_load_lds_dwordx4 v[0:1], off
	v_lshl_or_b32 v0, s20, 2, v68
	s_and_b32 s21, s20, 31
	v_bitop3_b32 v0, v0, 15, v116 bitop3:0x48
	v_lshl_or_b32 v1, s21, 10, v2
	v_lshl_or_b32 v176, v0, 4, v1
	v_lshl_add_u64 v[0:1], s[14:15], 0, v[176:177]
	v_lshl_add_u64 v[0:1], v[0:1], 0, s[8:9]
	s_lshl_b32 m0, s20, 10
	s_add_i32 s20, s18, 56
	global_load_lds_dwordx4 v[0:1], off
	v_lshl_or_b32 v0, s20, 2, v68
	s_and_b32 s21, s20, 31
	v_bitop3_b32 v0, v0, 15, v116 bitop3:0x48
	v_lshl_or_b32 v1, s21, 10, v2
	v_lshl_or_b32 v176, v0, 4, v1
	v_lshl_add_u64 v[0:1], s[14:15], 0, v[176:177]
	s_add_i32 s14, s18, 64
	s_lshl_b32 s15, s14, 2
	v_lshl_add_u64 v[0:1], v[0:1], 0, s[8:9]
	s_lshl_b32 m0, s20, 10
	s_and_b32 s15, s15, 0x7c
	global_load_lds_dwordx4 v[0:1], off
	v_or_b32_e32 v0, s15, v68
	v_bitop3_b32 v2, s15, v116, v68 bitop3:0x36
	v_lshlrev_b32_e32 v176, 8, v0
	v_lshlrev_b32_e32 v2, 4, v2
	s_lshl_b32 m0, s14, 10
	s_add_i32 s14, s18, 0x48
	v_lshl_add_u64 v[0:1], s[4:5], 0, v[176:177]
	v_and_b32_e32 v176, 0xf0, v2
	s_lshl_b32 s15, s14, 2
	v_lshl_add_u64 v[0:1], v[0:1], 0, v[176:177]
	s_and_b32 s15, s15, 0x7c
	global_load_lds_dwordx4 v[0:1], off
	v_or_b32_e32 v0, s15, v68
	v_bitop3_b32 v2, s15, v116, v68 bitop3:0x36
	v_lshlrev_b32_e32 v176, 8, v0
	v_lshlrev_b32_e32 v2, 4, v2
	s_lshl_b32 m0, s14, 10
	s_add_i32 s14, s18, 0x50
	v_lshl_add_u64 v[0:1], s[4:5], 0, v[176:177]
	v_and_b32_e32 v176, 0xf0, v2
	s_lshl_b32 s15, s14, 2
	v_lshl_add_u64 v[0:1], v[0:1], 0, v[176:177]
	s_and_b32 s15, s15, 0x7c
	global_load_lds_dwordx4 v[0:1], off
	v_or_b32_e32 v0, s15, v68
	v_bitop3_b32 v2, s15, v116, v68 bitop3:0x36
	v_lshlrev_b32_e32 v176, 8, v0
	v_lshlrev_b32_e32 v2, 4, v2
	s_lshl_b32 m0, s14, 10
	s_add_i32 s14, s18, 0x58
	v_lshl_add_u64 v[0:1], s[4:5], 0, v[176:177]
	v_and_b32_e32 v176, 0xf0, v2
	s_lshl_b32 s15, s14, 2
	v_lshl_add_u64 v[0:1], v[0:1], 0, v[176:177]
	s_and_b32 s15, s15, 0x7c
	global_load_lds_dwordx4 v[0:1], off
; #define SBAR() __builtin_amdgcn_sched_barrier(0)
; #define WAIT_V0() asm volatile("s_waitcnt vmcnt(0)" ::: "memory")
; #define RQ ((bfraw*)(kargs()->ws + O_RQ))
; #define RK ((bfraw*)(kargs()->ws + O_RK))
; #define RVT ((bfraw*)(kargs()->ws + O_RVT))
; #define ST ((bfraw*)(kargs()->ws + O_ST))
; __global__ void __launch_bounds__(512) mega(Params p) {
;     ...
;           { const bfraw* kb = RK + tok0 * 1024 + head * 128; const bfraw* vb = RVT + ((long)(chunk * 8 + head) * 128) * 128;
;             const bfraw* sfb = ST + ((long)((chunk * 8 + head) * 2)) * 16384;
;             const int wz = w;
; #pragma unroll
;             for (int g = 0; g < 16; ++g) { const int blk = g * 8 + wz, row = (blk & 31) * 4 + (lz >> 4), c = (lz ^ row) & 15;
;               const bfraw* sp = (g < 4) ? kb + (long)row * 1024 + c * 8 : (g < 8) ? vb + row * 128 + c * 8 : sfb + (g < 12 ? 0 : 16384) + row * 128 + c * 8;
;               __builtin_amdgcn_global_load_lds((const unsigned*)sp, (unsigned*)(shm + blk * 1024), 16, 0, 0); } }
;           bf16x8 qf[4];
;           { const bfraw* qp = RQ + (tok0 + w * 16 + fr) * 1024 + head * 128 + fq * 8;
; #pragma unroll
;             for (int sx = 0; sx < 4; ++sx) qf[sx] = *(const bf16x8*)(qp + sx * 32); }
;           WAIT_V0(); __syncthreads();
;           f32x4 o[8];
;           { f32x4 af[8] = {}, ab[8] = {};
; #pragma unroll
;             for (int ne = 0; ne < 8; ++ne) { bf16x8 Bf[4], Bb[4];
; #pragma unroll
;               for (int sx = 0; sx < 4; ++sx) { Bf[sx] = RLD16(2, ne * 16 + fr, sx * 4 + fq); Bb[sx] = RLD16(3, ne * 16 + fr, sx * 4 + fq); }
;               SBAR();
; #pragma unroll
;               for (int sx = 0; sx < 4; ++sx) { af[ne] = __builtin_amdgcn_mfma_f32_16x16x32_bf16(qf[sx], Bf[sx], af[ne], 0, 0, 0);
;                 ab[ne] = __builtin_amdgcn_mfma_f32_16x16x32_bf16(qf[sx], Bb[sx], ab[ne], 0, 0, 0); }
;               SBAR(); }
	v_or_b32_e32 v0, s15, v68
	v_bitop3_b32 v2, s15, v116, v68 bitop3:0x36
	v_lshlrev_b32_e32 v176, 8, v0
	v_lshlrev_b32_e32 v2, 4, v2
	s_lshl_b32 m0, s14, 10
	s_add_i32 s14, s18, 0x60
	v_lshl_add_u64 v[0:1], s[4:5], 0, v[176:177]
	v_and_b32_e32 v176, 0xf0, v2
	s_lshl_b32 s4, s14, 2
	v_lshl_add_u64 v[0:1], v[0:1], 0, v[176:177]
	s_and_b32 s4, s4, 0x7c
	global_load_lds_dwordx4 v[0:1], off
	v_or_b32_e32 v0, s4, v68
	v_bitop3_b32 v2, s4, v116, v68 bitop3:0x36
	s_add_u32 s4, s7, 0x30728000
	s_addc_u32 s5, s19, 0
	v_lshlrev_b32_e32 v176, 8, v0
	v_lshlrev_b32_e32 v2, 4, v2
	s_add_i32 s7, s18, 0x68
	v_lshl_add_u64 v[0:1], s[4:5], 0, v[176:177]
	v_and_b32_e32 v176, 0xf0, v2
	s_lshl_b32 m0, s14, 10
	s_lshl_b32 s14, s7, 2
	v_lshl_add_u64 v[0:1], v[0:1], 0, v[176:177]
	s_and_b32 s14, s14, 0x7c
	global_load_lds_dwordx4 v[0:1], off
	v_or_b32_e32 v0, s14, v68
	v_bitop3_b32 v2, s14, v116, v68 bitop3:0x36
	v_lshlrev_b32_e32 v176, 8, v0
	v_lshlrev_b32_e32 v2, 4, v2
	s_lshl_b32 m0, s7, 10
	s_add_i32 s7, s18, 0x70
	v_lshl_add_u64 v[0:1], s[4:5], 0, v[176:177]
	v_and_b32_e32 v176, 0xf0, v2
	s_lshl_b32 s14, s7, 2
	v_lshl_add_u64 v[0:1], v[0:1], 0, v[176:177]
	s_and_b32 s14, s14, 0x7c
	global_load_lds_dwordx4 v[0:1], off
	v_or_b32_e32 v0, s14, v68
	v_bitop3_b32 v2, s14, v116, v68 bitop3:0x36
	v_lshlrev_b32_e32 v176, 8, v0
	v_lshlrev_b32_e32 v2, 4, v2
	s_lshl_b32 m0, s7, 10
	s_add_i32 s7, s18, 0x78
	v_lshl_add_u64 v[0:1], s[4:5], 0, v[176:177]
	v_and_b32_e32 v176, 0xf0, v2
	s_lshl_b32 s14, s7, 2
	v_lshl_add_u64 v[0:1], v[0:1], 0, v[176:177]
	s_and_b32 s14, s14, 0x7c
	global_load_lds_dwordx4 v[0:1], off
	v_or_b32_e32 v0, s14, v68
	v_bitop3_b32 v2, s14, v116, v68 bitop3:0x36
	v_lshlrev_b32_e32 v176, 8, v0
	v_lshlrev_b32_e32 v2, 4, v2
	v_lshl_add_u64 v[0:1], s[4:5], 0, v[176:177]
	v_and_b32_e32 v176, 0xf0, v2
	v_lshl_add_u64 v[0:1], v[0:1], 0, v[176:177]
	s_lshl_b32 m0, s7, 10
	s_lshl_b64 s[4:5], s[2:3], 7
	s_mov_b64 s[2:3], s[0:1]
	global_load_lds_dwordx4 v[0:1], off
	s_load_dwordx2 s[14:15], s[2:3], 0xe8
	s_lshl_b32 s2, s18, 4
	s_ashr_i32 s3, s2, 31
	s_add_u32 s7, s4, s2
	s_addc_u32 s3, s5, s3
	v_or_b32_e32 v104, s7, v115
	v_mov_b32_e32 v105, s3
	v_lshlrev_b64 v[0:1], 11, v[104:105]
	s_waitcnt lgkmcnt(0)
	v_lshl_add_u64 v[0:1], s[14:15], 0, v[0:1]
	v_lshl_add_u64 v[0:1], v[0:1], 0, s[12:13]
	v_lshlrev_b32_e32 v176, 4, v68
	v_lshl_add_u64 v[0:1], v[0:1], 0, v[176:177]
	v_lshl_add_u64 v[2:3], v[0:1], 0, s[24:25]
	v_add_co_u32_e32 v0, vcc, s84, v0
	v_or_b32_e32 v24, 0x10000, v120
	s_nop 0
	v_addc_co_u32_e32 v1, vcc, 0, v1, vcc
	global_load_dwordx4 v[64:67], v[2:3], off offset:64
	global_load_dwordx4 v[84:87], v[2:3], off offset:128
	global_load_dwordx4 v[92:95], v[0:1], off
	global_load_dwordx4 v[88:91], v[2:3], off offset:192
	v_bitop3_b32 v0, v119, v115, 3 bitop3:0x6c
	v_or_b32_e32 v25, 0x18000, v120
	v_lshlrev_b32_e32 v69, 4, v0
	v_lshlrev_b32_e32 v82, 4, v8
	v_lshlrev_b32_e32 v83, 4, v16
	v_lshlrev_b32_e32 v121, 4, v26
	v_or_b32_e32 v0, v24, v69
	v_or_b32_e32 v4, v25, v69
	v_or_b32_e32 v8, v24, v82
	v_or_b32_e32 v12, v25, v82
	v_or_b32_e32 v16, v24, v83
	v_or_b32_e32 v20, v25, v83
	v_or_b32_e32 v24, v24, v121
	s_waitcnt vmcnt(0)
	s_waitcnt vmcnt(0)
	s_barrier
	ds_read_b128 v[0:3], v0
	ds_read_b128 v[4:7], v4
	ds_read_b128 v[8:11], v8
	ds_read_b128 v[12:15], v12
	ds_read_b128 v[16:19], v16
	ds_read_b128 v[20:23], v20
	v_or_b32_e32 v28, v25, v121
	ds_read_b128 v[24:27], v24
	ds_read_b128 v[32:35], v28
	s_waitcnt lgkmcnt(7)
	v_mfma_f32_16x16x32_bf16 v[0:3], v[92:95], v[0:3], 0
	s_waitcnt lgkmcnt(6)
	v_mfma_f32_16x16x32_bf16 v[4:7], v[92:95], v[4:7], 0
	s_waitcnt lgkmcnt(5)
	v_mfma_f32_16x16x32_bf16 v[0:3], v[64:67], v[8:11], v[0:3]
	s_waitcnt lgkmcnt(4)
	v_mfma_f32_16x16x32_bf16 v[4:7], v[64:67], v[12:15], v[4:7]
	s_waitcnt lgkmcnt(3)
	v_mfma_f32_16x16x32_bf16 v[0:3], v[84:87], v[16:19], v[0:3]
	s_waitcnt lgkmcnt(2)
	v_mfma_f32_16x16x32_bf16 v[4:7], v[84:87], v[20:23], v[4:7]
	s_waitcnt lgkmcnt(1)
	v_mfma_f32_16x16x32_bf16 v[28:31], v[88:91], v[24:27], v[0:3]
	s_waitcnt lgkmcnt(0)
	v_mfma_f32_16x16x32_bf16 v[60:63], v[88:91], v[32:35], v[4:7]
	v_or_b32_e32 v24, 0x1000, v120
	v_or_b32_e32 v100, 0x10000, v69
	v_or_b32_e32 v101, 0x18000, v69
	v_or_b32_e32 v102, 0x10000, v82
	v_or_b32_e32 v103, 0x18000, v82
	v_or_b32_e32 v104, 0x10000, v83
	v_or_b32_e32 v106, 0x18000, v83
	v_or_b32_e32 v107, 0x10000, v121
	v_or_b32_e32 v108, 0x18000, v121
	v_or_b32_e32 v0, v100, v24
	v_or_b32_e32 v4, v101, v24
	v_or_b32_e32 v8, v102, v24
	v_or_b32_e32 v12, v103, v24
	v_or_b32_e32 v16, v104, v24
	v_or_b32_e32 v20, v106, v24
	v_or_b32_e32 v25, v107, v24
	v_or_b32_e32 v32, v108, v24
	ds_read_b128 v[0:3], v0
	ds_read_b128 v[4:7], v4
	ds_read_b128 v[8:11], v8
	ds_read_b128 v[12:15], v12
	ds_read_b128 v[16:19], v16
	ds_read_b128 v[20:23], v20
	ds_read_b128 v[24:27], v25
	ds_read_b128 v[32:35], v32
	s_waitcnt lgkmcnt(7)
	v_mfma_f32_16x16x32_bf16 v[0:3], v[92:95], v[0:3], 0
	s_waitcnt lgkmcnt(6)
	v_mfma_f32_16x16x32_bf16 v[4:7], v[92:95], v[4:7], 0
	s_waitcnt lgkmcnt(5)
	v_mfma_f32_16x16x32_bf16 v[0:3], v[64:67], v[8:11], v[0:3]
	s_waitcnt lgkmcnt(4)
	v_mfma_f32_16x16x32_bf16 v[4:7], v[64:67], v[12:15], v[4:7]
	s_waitcnt lgkmcnt(3)
	v_mfma_f32_16x16x32_bf16 v[0:3], v[84:87], v[16:19], v[0:3]
	s_waitcnt lgkmcnt(2)
	v_mfma_f32_16x16x32_bf16 v[4:7], v[84:87], v[20:23], v[4:7]
	s_waitcnt lgkmcnt(1)
	v_mfma_f32_16x16x32_bf16 v[0:3], v[88:91], v[24:27], v[0:3]
	s_waitcnt lgkmcnt(0)
; #define SBAR() __builtin_amdgcn_sched_barrier(0)
; __global__ void __launch_bounds__(512) mega(Params p) {
;     ...
;             for (int ne = 0; ne < 8; ++ne) { bf16x8 Bf[4], Bb[4];
; #pragma unroll
;               for (int sx = 0; sx < 4; ++sx) { Bf[sx] = RLD16(2, ne * 16 + fr, sx * 4 + fq); Bb[sx] = RLD16(3, ne * 16 + fr, sx * 4 + fq); }
;               SBAR();
; #pragma unroll
;               for (int sx = 0; sx < 4; ++sx) { af[ne] = __builtin_amdgcn_mfma_f32_16x16x32_bf16(qf[sx], Bf[sx], af[ne], 0, 0, 0);
;                 ab[ne] = __builtin_amdgcn_mfma_f32_16x16x32_bf16(qf[sx], Bb[sx], ab[ne], 0, 0, 0); }
;               SBAR(); }
	v_mfma_f32_16x16x32_bf16 v[56:59], v[88:91], v[32:35], v[4:7]
	v_or_b32_e32 v32, 0x2000, v120
	s_nop 2
	v_or_b32_e32 v4, v100, v32
	v_or_b32_e32 v8, v101, v32
	v_or_b32_e32 v12, v102, v32
	v_or_b32_e32 v16, v103, v32
	v_or_b32_e32 v20, v104, v32
	v_or_b32_e32 v24, v106, v32
	v_or_b32_e32 v33, v107, v32
	v_or_b32_e32 v36, v108, v32
	ds_read_b128 v[4:7], v4
	ds_read_b128 v[8:11], v8
	ds_read_b128 v[12:15], v12
	ds_read_b128 v[16:19], v16
	ds_read_b128 v[20:23], v20
	ds_read_b128 v[24:27], v24
	ds_read_b128 v[32:35], v33
	ds_read_b128 v[36:39], v36
	s_waitcnt lgkmcnt(7)
	v_mfma_f32_16x16x32_bf16 v[4:7], v[92:95], v[4:7], 0
	s_waitcnt lgkmcnt(6)
	v_mfma_f32_16x16x32_bf16 v[8:11], v[92:95], v[8:11], 0
	s_waitcnt lgkmcnt(5)
	v_mfma_f32_16x16x32_bf16 v[4:7], v[64:67], v[12:15], v[4:7]
	s_waitcnt lgkmcnt(4)
	v_mfma_f32_16x16x32_bf16 v[8:11], v[64:67], v[16:19], v[8:11]
	s_waitcnt lgkmcnt(3)
	v_mfma_f32_16x16x32_bf16 v[4:7], v[84:87], v[20:23], v[4:7]
	s_waitcnt lgkmcnt(2)
	v_mfma_f32_16x16x32_bf16 v[8:11], v[84:87], v[24:27], v[8:11]
	s_waitcnt lgkmcnt(1)
	v_mfma_f32_16x16x32_bf16 v[4:7], v[88:91], v[32:35], v[4:7]
	s_waitcnt lgkmcnt(0)
	v_mfma_f32_16x16x32_bf16 v[52:55], v[88:91], v[36:39], v[8:11]
	v_or_b32_e32 v36, 0x3000, v120
	s_nop 2
	v_or_b32_e32 v8, v100, v36
	v_or_b32_e32 v12, v101, v36
	v_or_b32_e32 v16, v102, v36
	v_or_b32_e32 v20, v103, v36
	v_or_b32_e32 v24, v104, v36
	v_or_b32_e32 v32, v106, v36
	v_or_b32_e32 v37, v107, v36
	v_or_b32_e32 v40, v108, v36
	ds_read_b128 v[8:11], v8
	ds_read_b128 v[12:15], v12
	ds_read_b128 v[16:19], v16
	ds_read_b128 v[20:23], v20
	ds_read_b128 v[24:27], v24
	ds_read_b128 v[32:35], v32
	ds_read_b128 v[36:39], v37
	ds_read_b128 v[40:43], v40
	s_waitcnt lgkmcnt(7)
	v_mfma_f32_16x16x32_bf16 v[8:11], v[92:95], v[8:11], 0
	s_waitcnt lgkmcnt(6)
	v_mfma_f32_16x16x32_bf16 v[12:15], v[92:95], v[12:15], 0
	s_waitcnt lgkmcnt(5)
	v_mfma_f32_16x16x32_bf16 v[8:11], v[64:67], v[16:19], v[8:11]
	s_waitcnt lgkmcnt(4)
	v_mfma_f32_16x16x32_bf16 v[12:15], v[64:67], v[20:23], v[12:15]
	s_waitcnt lgkmcnt(3)
	v_mfma_f32_16x16x32_bf16 v[8:11], v[84:87], v[24:27], v[8:11]
	s_waitcnt lgkmcnt(2)
	v_mfma_f32_16x16x32_bf16 v[12:15], v[84:87], v[32:35], v[12:15]
	s_waitcnt lgkmcnt(1)
	v_mfma_f32_16x16x32_bf16 v[8:11], v[88:91], v[36:39], v[8:11]
	s_waitcnt lgkmcnt(0)
	v_mfma_f32_16x16x32_bf16 v[48:51], v[88:91], v[40:43], v[12:15]
	v_or_b32_e32 v40, 0x4000, v120
	s_nop 2
	v_or_b32_e32 v12, v100, v40
	v_or_b32_e32 v16, v101, v40
	v_or_b32_e32 v20, v102, v40
	v_or_b32_e32 v24, v103, v40
	v_or_b32_e32 v32, v104, v40
	v_or_b32_e32 v36, v106, v40
	v_or_b32_e32 v41, v107, v40
	v_or_b32_e32 v44, v108, v40
	ds_read_b128 v[12:15], v12
	ds_read_b128 v[16:19], v16
	ds_read_b128 v[20:23], v20
	ds_read_b128 v[24:27], v24
	ds_read_b128 v[32:35], v32
	ds_read_b128 v[36:39], v36
	ds_read_b128 v[40:43], v41
	ds_read_b128 v[44:47], v44
	s_waitcnt lgkmcnt(7)
	v_mfma_f32_16x16x32_bf16 v[12:15], v[92:95], v[12:15], 0
	s_waitcnt lgkmcnt(6)
	v_mfma_f32_16x16x32_bf16 v[16:19], v[92:95], v[16:19], 0
	s_waitcnt lgkmcnt(5)
	v_mfma_f32_16x16x32_bf16 v[12:15], v[64:67], v[20:23], v[12:15]
	s_waitcnt lgkmcnt(4)
	v_mfma_f32_16x16x32_bf16 v[16:19], v[64:67], v[24:27], v[16:19]
	s_waitcnt lgkmcnt(3)
	v_mfma_f32_16x16x32_bf16 v[12:15], v[84:87], v[32:35], v[12:15]
	s_waitcnt lgkmcnt(2)
	v_mfma_f32_16x16x32_bf16 v[16:19], v[84:87], v[36:39], v[16:19]
	s_waitcnt lgkmcnt(1)
	v_mfma_f32_16x16x32_bf16 v[12:15], v[88:91], v[40:43], v[12:15]
	s_waitcnt lgkmcnt(0)
	v_mfma_f32_16x16x32_bf16 v[44:47], v[88:91], v[44:47], v[16:19]
	v_or_b32_e32 v70, 0x5000, v120
	s_nop 2
	v_or_b32_e32 v16, v100, v70
	v_or_b32_e32 v20, v101, v70
	v_or_b32_e32 v24, v102, v70
	v_or_b32_e32 v32, v103, v70
	v_or_b32_e32 v36, v104, v70
	v_or_b32_e32 v40, v106, v70
	v_or_b32_e32 v71, v107, v70
	v_or_b32_e32 v74, v108, v70
	ds_read_b128 v[16:19], v16
	ds_read_b128 v[20:23], v20
	ds_read_b128 v[24:27], v24
	ds_read_b128 v[32:35], v32
	ds_read_b128 v[36:39], v36
	ds_read_b128 v[40:43], v40
	ds_read_b128 v[70:73], v71
	ds_read_b128 v[74:77], v74
	s_waitcnt lgkmcnt(7)
	v_mfma_f32_16x16x32_bf16 v[16:19], v[92:95], v[16:19], 0
	s_waitcnt lgkmcnt(6)
	v_mfma_f32_16x16x32_bf16 v[20:23], v[92:95], v[20:23], 0
	s_waitcnt lgkmcnt(5)
	v_mfma_f32_16x16x32_bf16 v[16:19], v[64:67], v[24:27], v[16:19]
	s_waitcnt lgkmcnt(4)
	v_mfma_f32_16x16x32_bf16 v[20:23], v[64:67], v[32:35], v[20:23]
	s_waitcnt lgkmcnt(3)
	v_mfma_f32_16x16x32_bf16 v[16:19], v[84:87], v[36:39], v[16:19]
	s_waitcnt lgkmcnt(2)
	v_mfma_f32_16x16x32_bf16 v[20:23], v[84:87], v[40:43], v[20:23]
	s_waitcnt lgkmcnt(1)
	v_mfma_f32_16x16x32_bf16 v[16:19], v[88:91], v[70:73], v[16:19]
	s_waitcnt lgkmcnt(0)
	v_mfma_f32_16x16x32_bf16 v[40:43], v[88:91], v[74:77], v[20:23]
	v_or_b32_e32 v78, 0x6000, v120
	s_nop 2
	v_or_b32_e32 v20, v100, v78
	v_or_b32_e32 v24, v101, v78
	v_or_b32_e32 v32, v102, v78
	v_or_b32_e32 v36, v103, v78
	v_or_b32_e32 v70, v104, v78
	v_or_b32_e32 v74, v106, v78
	v_or_b32_e32 v79, v107, v78
	v_or_b32_e32 v96, v108, v78
	ds_read_b128 v[20:23], v20
	ds_read_b128 v[24:27], v24
	ds_read_b128 v[32:35], v32
	ds_read_b128 v[36:39], v36
	ds_read_b128 v[70:73], v70
	ds_read_b128 v[74:77], v74
	ds_read_b128 v[78:81], v79
	ds_read_b128 v[96:99], v96
	s_waitcnt lgkmcnt(7)
	v_mfma_f32_16x16x32_bf16 v[20:23], v[92:95], v[20:23], 0
	s_waitcnt lgkmcnt(6)
	v_mfma_f32_16x16x32_bf16 v[24:27], v[92:95], v[24:27], 0
	s_waitcnt lgkmcnt(5)
	v_mfma_f32_16x16x32_bf16 v[20:23], v[64:67], v[32:35], v[20:23]
	s_waitcnt lgkmcnt(4)
	v_mfma_f32_16x16x32_bf16 v[24:27], v[64:67], v[36:39], v[24:27]
	s_waitcnt lgkmcnt(3)
	v_mfma_f32_16x16x32_bf16 v[20:23], v[84:87], v[70:73], v[20:23]
	s_waitcnt lgkmcnt(2)
; #define SBAR() __builtin_amdgcn_sched_barrier(0)
; __global__ void __launch_bounds__(512) mega(Params p) {
;     ...
;             for (int ne = 0; ne < 8; ++ne) { bf16x8 Bf[4], Bb[4];
; #pragma unroll
;               for (int sx = 0; sx < 4; ++sx) { Bf[sx] = RLD16(2, ne * 16 + fr, sx * 4 + fq); Bb[sx] = RLD16(3, ne * 16 + fr, sx * 4 + fq); }
;               SBAR();
; #pragma unroll
;               for (int sx = 0; sx < 4; ++sx) { af[ne] = __builtin_amdgcn_mfma_f32_16x16x32_bf16(qf[sx], Bf[sx], af[ne], 0, 0, 0);
;                 ab[ne] = __builtin_amdgcn_mfma_f32_16x16x32_bf16(qf[sx], Bb[sx], ab[ne], 0, 0, 0); }
;               SBAR(); }
; #pragma unroll
;             for (int j = 0; j < 4; ++j) { const int c = w * 16 + fq * 4 + j; const float xf = __expf(lgf * (float)(c + 1)), xb = __expf(lgb * (float)(128 - c));
; #pragma unroll
;               for (int ne = 0; ne < 8; ++ne) o[ne][j] = xf * af[ne][j] + xb * ab[ne][j]; } }
;           bf16x8 pf[4];
;           { f32x4 sc[8] = {};
; #pragma unroll
;             for (int n2 = 0; n2 < 4; ++n2) { bf16x8 A[2][4];
; #pragma unroll
;               for (int q2 = 0; q2 < 2; ++q2)
; #pragma unroll
;                 for (int sx = 0; sx < 4; ++sx) A[q2][sx] = RLD16(0, (n2 * 2 + q2) * 16 + fr, sx * 4 + fq);
;               SBAR();
; #pragma unroll
;               for (int q2 = 0; q2 < 2; ++q2)
; #pragma unroll
;                 for (int sx = 0; sx < 4; ++sx) sc[n2 * 2 + q2] = __builtin_amdgcn_mfma_f32_16x16x32_bf16(A[q2][sx], qf[sx], sc[n2 * 2 + q2], 0, 0, 0);
;               SBAR(); }
	v_mfma_f32_16x16x32_bf16 v[24:27], v[84:87], v[74:77], v[24:27]
	s_waitcnt lgkmcnt(1)
	v_mfma_f32_16x16x32_bf16 v[20:23], v[88:91], v[78:81], v[20:23]
	s_waitcnt lgkmcnt(0)
	v_mfma_f32_16x16x32_bf16 v[36:39], v[88:91], v[96:99], v[24:27]
	v_or_b32_e32 v109, 0x7000, v120
	s_nop 2
	v_or_b32_e32 v24, v100, v109
	v_or_b32_e32 v32, v101, v109
	v_or_b32_e32 v70, v102, v109
	v_or_b32_e32 v74, v103, v109
	v_or_b32_e32 v78, v104, v109
	v_or_b32_e32 v96, v106, v109
	v_or_b32_e32 v100, v107, v109
	ds_read_b128 v[24:27], v24
	ds_read_b128 v[32:35], v32
	ds_read_b128 v[70:73], v70
	ds_read_b128 v[74:77], v74
	ds_read_b128 v[78:81], v78
	ds_read_b128 v[96:99], v96
	v_or_b32_e32 v104, v108, v109
	ds_read_b128 v[100:103], v100
	ds_read_b128 v[106:109], v104
	s_waitcnt lgkmcnt(7)
	v_mfma_f32_16x16x32_bf16 v[24:27], v[92:95], v[24:27], 0
	s_waitcnt lgkmcnt(6)
	v_mfma_f32_16x16x32_bf16 v[32:35], v[92:95], v[32:35], 0
	s_waitcnt lgkmcnt(5)
	v_mfma_f32_16x16x32_bf16 v[24:27], v[64:67], v[70:73], v[24:27]
	s_waitcnt lgkmcnt(4)
	v_mfma_f32_16x16x32_bf16 v[32:35], v[64:67], v[74:77], v[32:35]
	s_waitcnt lgkmcnt(3)
	v_mfma_f32_16x16x32_bf16 v[24:27], v[84:87], v[78:81], v[24:27]
	s_waitcnt lgkmcnt(2)
	v_mfma_f32_16x16x32_bf16 v[32:35], v[84:87], v[96:99], v[32:35]
	s_waitcnt lgkmcnt(1)
	v_mfma_f32_16x16x32_bf16 v[24:27], v[88:91], v[100:103], v[24:27]
	s_waitcnt lgkmcnt(0)
	v_mfma_f32_16x16x32_bf16 v[32:35], v[88:91], v[106:109], v[32:35]
	v_lshlrev_b32_e32 v104, 2, v68
	v_or_b32_e32 v68, s2, v104
	v_or_b32_e32 v70, 1, v68
	v_cvt_f32_i32_e32 v71, v70
	v_sub_u32_e32 v70, 0x80, v70
	v_cvt_f32_i32_e32 v70, v70
	v_or_b32_e32 v146, v120, v69
	v_mul_f32_e32 v71, v117, v71
	v_mul_f32_e32 v71, 0x3fb8aa3b, v71
	v_exp_f32_e32 v106, v71
	v_sub_u32_e32 v71, 0x80, v68
	v_cvt_f32_i32_e32 v71, v71
	v_mul_f32_e32 v70, v118, v70
	v_mul_f32_e32 v70, 0x3fb8aa3b, v70
	v_exp_f32_e32 v109, v70
	v_mul_f32_e32 v71, v118, v71
	v_mul_f32_e32 v71, 0x3fb8aa3b, v71
	v_exp_f32_e32 v108, v71
	v_or_b32_e32 v71, 2, v68
	v_or_b32_e32 v70, 3, v68
	v_add_u32_e32 v68, 4, v68
	v_cvt_f32_i32_e32 v68, v68
	v_cvt_f32_i32_e32 v72, v71
	v_sub_u32_e32 v71, 0x80, v71
	v_cvt_f32_i32_e32 v71, v71
	v_mul_f32_e32 v68, v117, v68
	v_mul_f32_e32 v72, v117, v72
	v_mul_f32_e32 v68, 0x3fb8aa3b, v68
	v_mul_f32_e32 v72, 0x3fb8aa3b, v72
	v_exp_f32_e32 v111, v68
	v_sub_u32_e32 v68, 0x80, v70
	v_exp_f32_e32 v107, v72
	v_cvt_f32_i32_e32 v72, v70
	v_cvt_f32_i32_e32 v68, v68
	v_mul_f32_e32 v71, v118, v71
	v_mul_f32_e32 v71, 0x3fb8aa3b, v71
	v_mul_f32_e32 v72, v117, v72
	v_mul_f32_e32 v68, v118, v68
	v_mul_f32_e32 v72, 0x3fb8aa3b, v72
	v_mul_f32_e32 v68, 0x3fb8aa3b, v68
	v_or_b32_e32 v147, v120, v82
	v_or_b32_e32 v148, v120, v83
	v_or_b32_e32 v121, v120, v121
	v_exp_f32_e32 v110, v72
	v_exp_f32_e32 v112, v71
	v_exp_f32_e32 v113, v68
	ds_read_b128 v[68:71], v146
	ds_read_b128 v[72:75], v147
	ds_read_b128 v[76:79], v148
	ds_read_b128 v[80:83], v121
	ds_read_b128 v[96:99], v146 offset:4096
	ds_read_b128 v[100:103], v147 offset:4096
	ds_read_b128 v[122:125], v148 offset:4096
	ds_read_b128 v[126:129], v121 offset:4096
	s_waitcnt lgkmcnt(7)
	v_mfma_f32_16x16x32_bf16 v[68:71], v[68:71], v[92:95], 0
	s_waitcnt lgkmcnt(6)
	v_mfma_f32_16x16x32_bf16 v[68:71], v[72:75], v[64:67], v[68:71]
	s_waitcnt lgkmcnt(5)
	v_mfma_f32_16x16x32_bf16 v[68:71], v[76:79], v[84:87], v[68:71]
	s_waitcnt lgkmcnt(4)
	v_mfma_f32_16x16x32_bf16 v[130:133], v[80:83], v[88:91], v[68:71]
	s_waitcnt lgkmcnt(3)
	v_mfma_f32_16x16x32_bf16 v[68:71], v[96:99], v[92:95], 0
	s_waitcnt lgkmcnt(2)
	v_mfma_f32_16x16x32_bf16 v[68:71], v[100:103], v[64:67], v[68:71]
	s_waitcnt lgkmcnt(1)
	v_mfma_f32_16x16x32_bf16 v[68:71], v[122:125], v[84:87], v[68:71]
	s_waitcnt lgkmcnt(0)
	v_mfma_f32_16x16x32_bf16 v[100:103], v[126:129], v[88:91], v[68:71]
	s_nop 5
	ds_read_b128 v[68:71], v146 offset:8192
	ds_read_b128 v[72:75], v146 offset:12288
	ds_read_b128 v[76:79], v147 offset:8192
	ds_read_b128 v[80:83], v147 offset:12288
	ds_read_b128 v[96:99], v148 offset:8192
	ds_read_b128 v[122:125], v148 offset:12288
	ds_read_b128 v[126:129], v121 offset:8192
	ds_read_b128 v[134:137], v121 offset:12288
	s_waitcnt lgkmcnt(7)
	v_mfma_f32_16x16x32_bf16 v[68:71], v[68:71], v[92:95], 0
	s_waitcnt lgkmcnt(5)
	v_mfma_f32_16x16x32_bf16 v[68:71], v[76:79], v[64:67], v[68:71]
	s_waitcnt lgkmcnt(3)
	v_mfma_f32_16x16x32_bf16 v[68:71], v[96:99], v[84:87], v[68:71]
	s_waitcnt lgkmcnt(1)
	v_mfma_f32_16x16x32_bf16 v[96:99], v[126:129], v[88:91], v[68:71]
	v_mfma_f32_16x16x32_bf16 v[68:71], v[72:75], v[92:95], 0
	v_mfma_f32_16x16x32_bf16 v[68:71], v[80:83], v[64:67], v[68:71]
	v_mfma_f32_16x16x32_bf16 v[68:71], v[122:125], v[84:87], v[68:71]
	s_waitcnt lgkmcnt(0)
	v_mfma_f32_16x16x32_bf16 v[80:83], v[134:137], v[88:91], v[68:71]
	s_nop 5
	ds_read_b128 v[68:71], v146 offset:16384
	ds_read_b128 v[72:75], v146 offset:20480
	ds_read_b128 v[76:79], v147 offset:16384
	ds_read_b128 v[122:125], v147 offset:20480
	ds_read_b128 v[126:129], v148 offset:16384
	ds_read_b128 v[134:137], v148 offset:20480
	ds_read_b128 v[138:141], v121 offset:16384
	ds_read_b128 v[142:145], v121 offset:20480
	s_waitcnt lgkmcnt(7)
	v_mfma_f32_16x16x32_bf16 v[68:71], v[68:71], v[92:95], 0
	s_waitcnt lgkmcnt(5)
	v_mfma_f32_16x16x32_bf16 v[68:71], v[76:79], v[64:67], v[68:71]
	s_waitcnt lgkmcnt(3)
	v_mfma_f32_16x16x32_bf16 v[68:71], v[126:129], v[84:87], v[68:71]
	s_waitcnt lgkmcnt(1)
	v_mfma_f32_16x16x32_bf16 v[76:79], v[138:141], v[88:91], v[68:71]
	v_mfma_f32_16x16x32_bf16 v[68:71], v[72:75], v[92:95], 0
	v_mfma_f32_16x16x32_bf16 v[68:71], v[122:125], v[64:67], v[68:71]
	v_mfma_f32_16x16x32_bf16 v[68:71], v[134:137], v[84:87], v[68:71]
	s_waitcnt lgkmcnt(0)
; DEVFI bfraw f2bf(float x) { unsigned u = __float_as_uint(x); u += 0x7fffu + ((u >> 16) & 1u); return (bfraw)(u >> 16); }
; __global__ void __launch_bounds__(512) mega(Params p) {
;     ...
;             const int cc = w * 16 + fr;
; #pragma unroll
;             for (int sx = 0; sx < 4; ++sx)
; #pragma unroll
;               for (int hf = 0; hf < 2; ++hf)
; #pragma unroll
;                 for (int j = 0; j < 4; ++j) { const int n = 2 * sx + hf, mm = n * 16 + fq * 4 + j, diff = cc - mm;
;                   const float Dm = (diff >= 0) ? __expf(lgf * (float)diff) : __expf(lgb * (float)(-diff));
;                   pf[sx][hf * 4 + j] = (short)f2bf(sc[n][j] * Dm); } }
	v_mfma_f32_16x16x32_bf16 v[72:75], v[142:145], v[88:91], v[68:71]
	s_nop 5
	ds_read_b128 v[68:71], v146 offset:24576
	ds_read_b128 v[122:125], v146 offset:28672
	ds_read_b128 v[126:129], v147 offset:24576
	ds_read_b128 v[134:137], v147 offset:28672
	ds_read_b128 v[138:141], v148 offset:24576
	ds_read_b128 v[142:145], v148 offset:28672
	ds_read_b128 v[146:149], v121 offset:24576
	ds_read_b128 v[150:153], v121 offset:28672
	s_waitcnt lgkmcnt(7)
	v_mfma_f32_16x16x32_bf16 v[68:71], v[68:71], v[92:95], 0
	s_waitcnt lgkmcnt(6)
	v_mfma_f32_16x16x32_bf16 v[92:95], v[122:125], v[92:95], 0
	s_waitcnt lgkmcnt(5)
	v_mfma_f32_16x16x32_bf16 v[68:71], v[126:129], v[64:67], v[68:71]
	s_waitcnt lgkmcnt(4)
	v_mfma_f32_16x16x32_bf16 v[64:67], v[134:137], v[64:67], v[92:95]
	s_waitcnt lgkmcnt(3)
	v_mfma_f32_16x16x32_bf16 v[68:71], v[138:141], v[84:87], v[68:71]
	s_waitcnt lgkmcnt(2)
	v_mfma_f32_16x16x32_bf16 v[64:67], v[142:145], v[84:87], v[64:67]
	s_waitcnt lgkmcnt(1)
	v_mfma_f32_16x16x32_bf16 v[68:71], v[146:149], v[88:91], v[68:71]
	s_waitcnt lgkmcnt(0)
	v_mfma_f32_16x16x32_bf16 v[64:67], v[150:153], v[88:91], v[64:67]
	v_or_b32_e32 v87, s2, v115
	v_sub_u32_e32 v84, v87, v104
	v_sub_u32_e32 v85, 0, v84
	v_max_i32_e32 v85, v84, v85
	v_cvt_f32_u32_e32 v85, v85
	v_cmp_gt_i32_e32 vcc, 0, v84
	v_or_b32_e32 v86, 1, v104
	s_nop 0
	v_cndmask_b32_e32 v84, v117, v118, vcc
	v_mul_f32_e32 v84, v84, v85
	v_sub_u32_e32 v85, v87, v86
	v_sub_u32_e32 v88, 0, v85
	v_max_i32_e32 v88, v85, v88
	v_cvt_f32_u32_e32 v88, v88
	v_cmp_gt_i32_e32 vcc, 0, v85
	v_mul_f32_e32 v84, 0x3fb8aa3b, v84
	v_exp_f32_e32 v84, v84
	v_cndmask_b32_e32 v85, v117, v118, vcc
	v_mul_f32_e32 v85, v85, v88
	v_mul_f32_e32 v85, 0x3fb8aa3b, v85
	v_exp_f32_e32 v85, v85
	s_nop 0
	v_pk_mul_f32 v[94:95], v[84:85], v[130:131]
	v_or_b32_e32 v85, 2, v104
	v_sub_u32_e32 v84, v87, v85
	v_sub_u32_e32 v88, 0, v84
	v_max_i32_e32 v88, v84, v88
	v_cvt_f32_u32_e32 v88, v88
	v_cmp_gt_i32_e32 vcc, 0, v84
	v_bfe_u32 v124, v94, 16, 1
	v_bfe_u32 v123, v95, 16, 1
	v_cndmask_b32_e32 v84, v117, v118, vcc
	v_mul_f32_e32 v84, v84, v88
	v_mul_f32_e32 v84, 0x3fb8aa3b, v84
	v_exp_f32_e32 v88, v84
	v_or_b32_e32 v84, 3, v104
	v_sub_u32_e32 v89, v87, v84
	v_sub_u32_e32 v90, 0, v89
	v_max_i32_e32 v90, v89, v90
	v_cvt_f32_u32_e32 v90, v90
	v_cmp_gt_i32_e32 vcc, 0, v89
	s_nop 1
	v_cndmask_b32_e32 v89, v117, v118, vcc
	v_mul_f32_e32 v89, v89, v90
	v_or_b32_e32 v90, 16, v104
	v_sub_u32_e32 v90, v87, v90
	v_sub_u32_e32 v91, 0, v90
	v_max_i32_e32 v91, v90, v91
	v_cvt_f32_u32_e32 v91, v91
	v_cmp_gt_i32_e32 vcc, 0, v90
	v_mul_f32_e32 v89, 0x3fb8aa3b, v89
	v_exp_f32_e32 v89, v89
	v_cndmask_b32_e32 v90, v117, v118, vcc
	v_mul_f32_e32 v90, v90, v91
	v_or_b32_e32 v91, 17, v104
	v_sub_u32_e32 v91, v87, v91
	v_sub_u32_e32 v92, 0, v91
	v_max_i32_e32 v92, v91, v92
	v_cvt_f32_u32_e32 v92, v92
	v_cmp_gt_i32_e32 vcc, 0, v91
	v_mul_f32_e32 v90, 0x3fb8aa3b, v90
	v_exp_f32_e32 v90, v90
	v_cndmask_b32_e32 v91, v117, v118, vcc
	v_mul_f32_e32 v91, v91, v92
	v_mul_f32_e32 v91, 0x3fb8aa3b, v91
	v_exp_f32_e32 v91, v91
	v_pk_mul_f32 v[88:89], v[88:89], v[132:133]
	v_pk_mul_f32 v[100:101], v[90:91], v[100:101]
	v_or_b32_e32 v90, 18, v104
	v_sub_u32_e32 v90, v87, v90
	v_sub_u32_e32 v91, 0, v90
	v_max_i32_e32 v91, v90, v91
	v_cvt_f32_u32_e32 v91, v91
	v_cmp_gt_i32_e32 vcc, 0, v90
	v_bfe_u32 v122, v100, 16, 1
	v_bfe_u32 v121, v101, 16, 1
	v_cndmask_b32_e32 v90, v117, v118, vcc
	v_mul_f32_e32 v90, v90, v91
	v_or_b32_e32 v91, 19, v104
	v_sub_u32_e32 v91, v87, v91
	v_sub_u32_e32 v92, 0, v91
	v_max_i32_e32 v92, v91, v92
	v_cvt_f32_u32_e32 v92, v92
	v_cmp_gt_i32_e32 vcc, 0, v91
	v_mul_f32_e32 v90, 0x3fb8aa3b, v90
	v_exp_f32_e32 v90, v90
	v_cndmask_b32_e32 v91, v117, v118, vcc
	v_mul_f32_e32 v91, v91, v92
	v_mul_f32_e32 v91, 0x3fb8aa3b, v91
	v_exp_f32_e32 v91, v91
	s_nop 0
	v_pk_mul_f32 v[92:93], v[90:91], v[102:103]
	s_nop 0
	v_bfe_u32 v90, v93, 16, 1
	v_add3_u32 v93, v93, v90, s82
	v_add3_u32 v90, v94, v124, s82
	v_add3_u32 v94, v100, v122, s82
	v_or_b32_e32 v100, 32, v104
	v_bfe_u32 v91, v92, 16, 1
	v_sub_u32_e32 v100, v87, v100
	v_add3_u32 v91, v92, v91, s82
	v_add3_u32 v92, v95, v123, s82
	v_add3_u32 v95, v101, v121, s82
	v_sub_u32_e32 v101, 0, v100
	v_max_i32_e32 v101, v100, v101
	v_cvt_f32_u32_e32 v101, v101
	v_cmp_gt_i32_e32 vcc, 0, v100
	v_bfe_u32 v102, v89, 16, 1
	v_add3_u32 v89, v89, v102, s82
	v_cndmask_b32_e32 v100, v117, v118, vcc
	v_mul_f32_e32 v100, v100, v101
	v_or_b32_e32 v101, 33, v104
	v_sub_u32_e32 v101, v87, v101
	v_sub_u32_e32 v102, 0, v101
	v_max_i32_e32 v102, v101, v102
	v_cvt_f32_u32_e32 v102, v102
	v_cmp_gt_i32_e32 vcc, 0, v101
	v_mul_f32_e32 v100, 0x3fb8aa3b, v100
	v_exp_f32_e32 v100, v100
	v_cndmask_b32_e32 v101, v117, v118, vcc
	v_mul_f32_e32 v101, v101, v102
	v_mul_f32_e32 v101, 0x3fb8aa3b, v101
	v_exp_f32_e32 v101, v101
	v_bfe_u32 v103, v88, 16, 1
	v_add3_u32 v88, v88, v103, s82
	v_pk_mul_f32 v[100:101], v[100:101], v[96:97]
	v_or_b32_e32 v96, 34, v104
	v_sub_u32_e32 v96, v87, v96
	v_sub_u32_e32 v97, 0, v96
	v_max_i32_e32 v97, v96, v97
	v_cvt_f32_u32_e32 v97, v97
	v_cmp_gt_i32_e32 vcc, 0, v96
	v_bfe_u32 v124, v100, 16, 1
	v_bfe_u32 v123, v101, 16, 1
	v_cndmask_b32_e32 v96, v117, v118, vcc
	v_mul_f32_e32 v96, v96, v97
	v_or_b32_e32 v97, 35, v104
	v_sub_u32_e32 v97, v87, v97
	v_sub_u32_e32 v102, 0, v97
	v_max_i32_e32 v102, v97, v102
	v_cvt_f32_u32_e32 v102, v102
	v_cmp_gt_i32_e32 vcc, 0, v97
	v_mul_f32_e32 v96, 0x3fb8aa3b, v96
	v_exp_f32_e32 v96, v96
	v_cndmask_b32_e32 v97, v117, v118, vcc
	v_mul_f32_e32 v97, v97, v102
	v_mul_f32_e32 v97, 0x3fb8aa3b, v97
	v_exp_f32_e32 v97, v97
	s_nop 0
	v_pk_mul_f32 v[96:97], v[96:97], v[98:99]
; DEVFI bfraw f2bf(float x) { unsigned u = __float_as_uint(x); u += 0x7fffu + ((u >> 16) & 1u); return (bfraw)(u >> 16); }
; __global__ void __launch_bounds__(512) mega(Params p) {
;     ...
;             const int cc = w * 16 + fr;
; #pragma unroll
;             for (int sx = 0; sx < 4; ++sx)
; #pragma unroll
;               for (int hf = 0; hf < 2; ++hf)
; #pragma unroll
;                 for (int j = 0; j < 4; ++j) { const int n = 2 * sx + hf, mm = n * 16 + fq * 4 + j, diff = cc - mm;
;                   const float Dm = (diff >= 0) ? __expf(lgf * (float)diff) : __expf(lgb * (float)(-diff));
;                   pf[sx][hf * 4 + j] = (short)f2bf(sc[n][j] * Dm); } }
	v_or_b32_e32 v98, 48, v104
	v_sub_u32_e32 v98, v87, v98
	v_sub_u32_e32 v99, 0, v98
	v_max_i32_e32 v99, v98, v99
	v_cvt_f32_u32_e32 v99, v99
	v_cmp_gt_i32_e32 vcc, 0, v98
	s_nop 1
	v_cndmask_b32_e32 v98, v117, v118, vcc
	v_mul_f32_e32 v98, v98, v99
	v_or_b32_e32 v99, 49, v104
	v_sub_u32_e32 v99, v87, v99
	v_sub_u32_e32 v102, 0, v99
	v_max_i32_e32 v102, v99, v102
	v_cvt_f32_u32_e32 v102, v102
	v_cmp_gt_i32_e32 vcc, 0, v99
	v_mul_f32_e32 v98, 0x3fb8aa3b, v98
	v_exp_f32_e32 v98, v98
	v_cndmask_b32_e32 v99, v117, v118, vcc
	v_mul_f32_e32 v99, v99, v102
	v_mul_f32_e32 v99, 0x3fb8aa3b, v99
	v_exp_f32_e32 v99, v99
	s_nop 0
	v_pk_mul_f32 v[98:99], v[98:99], v[80:81]
	v_or_b32_e32 v80, 50, v104
	v_sub_u32_e32 v80, v87, v80
	v_sub_u32_e32 v81, 0, v80
	v_max_i32_e32 v81, v80, v81
	v_cvt_f32_u32_e32 v81, v81
	v_cmp_gt_i32_e32 vcc, 0, v80
	v_bfe_u32 v122, v98, 16, 1
	v_add3_u32 v98, v98, v122, s82
	v_cndmask_b32_e32 v80, v117, v118, vcc
	v_mul_f32_e32 v80, v80, v81
	v_or_b32_e32 v81, 51, v104
	v_sub_u32_e32 v81, v87, v81
	v_sub_u32_e32 v102, 0, v81
	v_max_i32_e32 v102, v81, v102
	v_cvt_f32_u32_e32 v102, v102
	v_cmp_gt_i32_e32 vcc, 0, v81
	v_mul_f32_e32 v80, 0x3fb8aa3b, v80
	v_exp_f32_e32 v80, v80
	v_cndmask_b32_e32 v81, v117, v118, vcc
	v_mul_f32_e32 v81, v81, v102
	v_mul_f32_e32 v81, 0x3fb8aa3b, v81
	v_exp_f32_e32 v81, v81
	v_bfe_u32 v121, v99, 16, 1
	v_add3_u32 v99, v99, v121, s82
	v_pk_mul_f32 v[102:103], v[80:81], v[82:83]
	s_nop 0
	v_bfe_u32 v82, v103, 16, 1
	v_bfe_u32 v81, v97, 16, 1
	v_add3_u32 v81, v97, v81, s82
	v_add3_u32 v97, v103, v82, s82
	v_add3_u32 v82, v100, v124, s82
	v_or_b32_e32 v100, 64, v104
	v_bfe_u32 v80, v96, 16, 1
	v_sub_u32_e32 v100, v87, v100
	v_add3_u32 v80, v96, v80, s82
	v_add3_u32 v96, v101, v123, s82
	v_sub_u32_e32 v101, 0, v100
	v_max_i32_e32 v101, v100, v101
	v_cvt_f32_u32_e32 v101, v101
	v_cmp_gt_i32_e32 vcc, 0, v100
	v_bfe_u32 v83, v102, 16, 1
	v_add3_u32 v83, v102, v83, s82
	v_cndmask_b32_e32 v100, v117, v118, vcc
	v_mul_f32_e32 v100, v100, v101
	v_or_b32_e32 v101, 0x41, v104
	v_sub_u32_e32 v101, v87, v101
	v_sub_u32_e32 v102, 0, v101
	v_max_i32_e32 v102, v101, v102
	v_cvt_f32_u32_e32 v102, v102
	v_cmp_gt_i32_e32 vcc, 0, v101
	v_mul_f32_e32 v100, 0x3fb8aa3b, v100
	v_exp_f32_e32 v100, v100
	v_cndmask_b32_e32 v101, v117, v118, vcc
	v_mul_f32_e32 v101, v101, v102
	v_mul_f32_e32 v101, 0x3fb8aa3b, v101
	v_exp_f32_e32 v101, v101
	s_nop 0
	v_pk_mul_f32 v[76:77], v[100:101], v[76:77]
	v_or_b32_e32 v100, 0x42, v104
	v_sub_u32_e32 v100, v87, v100
	v_sub_u32_e32 v101, 0, v100
	v_max_i32_e32 v101, v100, v101
	v_cvt_f32_u32_e32 v101, v101
	v_cmp_gt_i32_e32 vcc, 0, v100
	v_bfe_u32 v123, v77, 16, 1
	v_bfe_u32 v124, v76, 16, 1
	v_cndmask_b32_e32 v100, v117, v118, vcc
	v_mul_f32_e32 v100, v100, v101
	v_or_b32_e32 v101, 0x43, v104
	v_sub_u32_e32 v101, v87, v101
	v_sub_u32_e32 v102, 0, v101
	v_max_i32_e32 v102, v101, v102
	v_cvt_f32_u32_e32 v102, v102
	v_cmp_gt_i32_e32 vcc, 0, v101
	v_mul_f32_e32 v100, 0x3fb8aa3b, v100
	v_exp_f32_e32 v100, v100
	v_cndmask_b32_e32 v101, v117, v118, vcc
	v_mul_f32_e32 v101, v101, v102
	v_mul_f32_e32 v101, 0x3fb8aa3b, v101
	v_exp_f32_e32 v101, v101
	v_add3_u32 v142, v76, v124, s82
	v_add3_u32 v143, v77, v123, s82
	v_pk_mul_f32 v[78:79], v[100:101], v[78:79]
	v_or_b32_e32 v100, 0x50, v104
	v_sub_u32_e32 v100, v87, v100
	v_sub_u32_e32 v101, 0, v100
	v_max_i32_e32 v101, v100, v101
	v_cvt_f32_u32_e32 v101, v101
	v_cmp_gt_i32_e32 vcc, 0, v100
	v_bfe_u32 v103, v78, 16, 1
	v_add3_u32 v78, v78, v103, s82
	v_cndmask_b32_e32 v100, v117, v118, vcc
	v_mul_f32_e32 v100, v100, v101
	v_or_b32_e32 v101, 0x51, v104
	v_sub_u32_e32 v101, v87, v101
	v_sub_u32_e32 v102, 0, v101
	v_max_i32_e32 v102, v101, v102
	v_cvt_f32_u32_e32 v102, v102
	v_cmp_gt_i32_e32 vcc, 0, v101
	v_mul_f32_e32 v100, 0x3fb8aa3b, v100
	v_exp_f32_e32 v100, v100
	v_cndmask_b32_e32 v101, v117, v118, vcc
	v_mul_f32_e32 v101, v101, v102
	v_mul_f32_e32 v101, 0x3fb8aa3b, v101
	v_exp_f32_e32 v101, v101
	s_nop 0
	v_pk_mul_f32 v[72:73], v[100:101], v[72:73]
	v_or_b32_e32 v100, 0x52, v104
	v_sub_u32_e32 v100, v87, v100
	v_sub_u32_e32 v101, 0, v100
	v_max_i32_e32 v101, v100, v101
	v_cvt_f32_u32_e32 v101, v101
	v_cmp_gt_i32_e32 vcc, 0, v100
	v_bfe_u32 v122, v72, 16, 1
	v_add3_u32 v144, v72, v122, s82
	v_cndmask_b32_e32 v100, v117, v118, vcc
	v_mul_f32_e32 v100, v100, v101
	v_or_b32_e32 v101, 0x53, v104
	v_sub_u32_e32 v101, v87, v101
	v_sub_u32_e32 v102, 0, v101
	v_max_i32_e32 v102, v101, v102
	v_cvt_f32_u32_e32 v102, v102
	v_cmp_gt_i32_e32 vcc, 0, v101
	v_or_b32_e32 v72, 0x60, v104
	v_bfe_u32 v121, v73, 16, 1
	v_cndmask_b32_e32 v101, v117, v118, vcc
	v_sub_u32_e32 v72, v87, v72
	v_mul_f32_e32 v101, v101, v102
	v_add3_u32 v145, v73, v121, s82
	v_sub_u32_e32 v73, 0, v72
	v_mul_f32_e32 v100, 0x3fb8aa3b, v100
	v_mul_f32_e32 v101, 0x3fb8aa3b, v101
	v_max_i32_e32 v73, v72, v73
	v_exp_f32_e32 v100, v100
	v_exp_f32_e32 v101, v101
	v_cvt_f32_u32_e32 v73, v73
	v_cmp_gt_i32_e32 vcc, 0, v72
	v_bfe_u32 v102, v79, 16, 1
	v_pk_mul_f32 v[74:75], v[100:101], v[74:75]
	v_cndmask_b32_e32 v72, v117, v118, vcc
	v_mul_f32_e32 v72, v72, v73
	v_or_b32_e32 v73, 0x61, v104
	v_bfe_u32 v101, v74, 16, 1
	v_sub_u32_e32 v73, v87, v73
	v_add3_u32 v140, v74, v101, s82
	v_sub_u32_e32 v74, 0, v73
	v_max_i32_e32 v74, v73, v74
	v_cvt_f32_u32_e32 v74, v74
	v_cmp_gt_i32_e32 vcc, 0, v73
	v_mul_f32_e32 v72, 0x3fb8aa3b, v72
	v_exp_f32_e32 v72, v72
	v_cndmask_b32_e32 v73, v117, v118, vcc
	v_mul_f32_e32 v73, v73, v74
	v_mul_f32_e32 v73, 0x3fb8aa3b, v73
	v_exp_f32_e32 v73, v73
	v_bfe_u32 v100, v75, 16, 1
	v_add3_u32 v141, v75, v100, s82
	v_add3_u32 v79, v79, v102, s82
	v_pk_mul_f32 v[68:69], v[72:73], v[68:69]
; #define SBAR() __builtin_amdgcn_sched_barrier(0)
; __global__ void __launch_bounds__(512) mega(Params p) {
;     ...
;             for (int j = 0; j < 4; ++j) { const int c = w * 16 + fq * 4 + j; const float xf = __expf(lgf * (float)(c + 1)), xb = __expf(lgb * (float)(128 - c));
; #pragma unroll
;               for (int ne = 0; ne < 8; ++ne) o[ne][j] = xf * af[ne][j] + xb * ab[ne][j]; } }
;     ...
;           { const char* vl = shm + 32768 + fr * 256 + (fq & 1) * 8;
; #pragma unroll
;             for (int n2 = 0; n2 < 4; ++n2) { s16x4 lo[2][4], hi[2][4];
; #pragma unroll
;               for (int q2 = 0; q2 < 2; ++q2)
; #pragma unroll
;                 for (int sx = 0; sx < 4; ++sx) { lo[q2][sx] = *(const s16x4*)(vl + (n2 * 2 + q2) * 4096 + ((((sx * 4 + (fq >> 1)) ^ fr) & 15) << 4));
;                   hi[q2][sx] = *(const s16x4*)(vl + (n2 * 2 + q2) * 4096 + ((((sx * 4 + 2 + (fq >> 1)) ^ fr) & 15) << 4)); }
;               SBAR();
; #pragma unroll
;               for (int q2 = 0; q2 < 2; ++q2)
; #pragma unroll
;                 for (int sx = 0; sx < 4; ++sx) { const bf16x8 B = {lo[q2][sx][0], lo[q2][sx][1], lo[q2][sx][2], lo[q2][sx][3], hi[q2][sx][0], hi[q2][sx][1], hi[q2][sx][2], hi[q2][sx][3]};
;                   o[n2 * 2 + q2] = __builtin_amdgcn_mfma_f32_16x16x32_bf16(pf[sx], B, o[n2 * 2 + q2], 0, 0, 0); }
;               SBAR(); } }
	v_or_b32_e32 v72, 0x62, v104
	v_sub_u32_e32 v72, v87, v72
	v_sub_u32_e32 v73, 0, v72
	v_max_i32_e32 v73, v72, v73
	v_cvt_f32_u32_e32 v73, v73
	v_cmp_gt_i32_e32 vcc, 0, v72
	v_bfe_u32 v100, v68, 16, 1
	v_add3_u32 v150, v68, v100, s82
	v_cndmask_b32_e32 v72, v117, v118, vcc
	v_mul_f32_e32 v72, v72, v73
	v_or_b32_e32 v73, 0x63, v104
	v_sub_u32_e32 v73, v87, v73
	v_sub_u32_e32 v74, 0, v73
	v_max_i32_e32 v74, v73, v74
	v_cvt_f32_u32_e32 v74, v74
	v_cmp_gt_i32_e32 vcc, 0, v73
	v_mul_f32_e32 v72, 0x3fb8aa3b, v72
	v_exp_f32_e32 v72, v72
	v_cndmask_b32_e32 v73, v117, v118, vcc
	v_mul_f32_e32 v73, v73, v74
	v_mul_f32_e32 v73, 0x3fb8aa3b, v73
	v_exp_f32_e32 v73, v73
	s_nop 0
	v_pk_mul_f32 v[70:71], v[72:73], v[70:71]
	v_or_b32_e32 v72, 0x70, v104
	v_sub_u32_e32 v72, v87, v72
	v_sub_u32_e32 v73, 0, v72
	v_max_i32_e32 v73, v72, v73
	v_cvt_f32_u32_e32 v73, v73
	v_cmp_gt_i32_e32 vcc, 0, v72
	v_bfe_u32 v75, v70, 16, 1
	v_add3_u32 v146, v70, v75, s82
	v_cndmask_b32_e32 v72, v117, v118, vcc
	v_mul_f32_e32 v72, v72, v73
	v_or_b32_e32 v73, 0x71, v104
	v_sub_u32_e32 v73, v87, v73
	v_sub_u32_e32 v74, 0, v73
	v_max_i32_e32 v74, v73, v74
	v_cvt_f32_u32_e32 v74, v74
	v_cmp_gt_i32_e32 vcc, 0, v73
	v_mul_f32_e32 v72, 0x3fb8aa3b, v72
	v_exp_f32_e32 v72, v72
	v_cndmask_b32_e32 v73, v117, v118, vcc
	v_mul_f32_e32 v73, v73, v74
	v_mul_f32_e32 v73, 0x3fb8aa3b, v73
	v_exp_f32_e32 v73, v73
	s_nop 0
	v_pk_mul_f32 v[64:65], v[72:73], v[64:65]
	v_or_b32_e32 v72, 0x72, v104
	v_sub_u32_e32 v72, v87, v72
	v_sub_u32_e32 v73, 0, v72
	v_max_i32_e32 v73, v72, v73
	v_cvt_f32_u32_e32 v73, v73
	v_cmp_gt_i32_e32 vcc, 0, v72
	v_bfe_u32 v76, v65, 16, 1
	v_bfe_u32 v77, v64, 16, 1
	v_cndmask_b32_e32 v72, v117, v118, vcc
	v_mul_f32_e32 v72, v72, v73
	v_or_b32_e32 v73, 0x73, v104
	v_sub_u32_e32 v73, v87, v73
	v_sub_u32_e32 v74, 0, v73
	v_max_i32_e32 v74, v73, v74
	v_cvt_f32_u32_e32 v74, v74
	v_cmp_gt_i32_e32 vcc, 0, v73
	v_mul_f32_e32 v72, 0x3fb8aa3b, v72
	v_exp_f32_e32 v72, v72
	v_cndmask_b32_e32 v73, v117, v118, vcc
	v_mul_f32_e32 v73, v73, v74
	v_mul_f32_e32 v73, 0x3fb8aa3b, v73
	v_exp_f32_e32 v73, v73
	v_add3_u32 v151, v64, v77, s82
	v_add3_u32 v152, v65, v76, s82
	v_lshrrev_b32_e32 v64, 1, v116
	v_pk_mul_f32 v[66:67], v[72:73], v[66:67]
	v_bfe_u32 v65, v119, 1, 1
	v_bfe_u32 v73, v66, 16, 1
	v_add3_u32 v148, v66, v73, s82
	v_and_or_b32 v64, v64, 8, v120
	v_bitop3_b32 v66, v65, v116, 15 bitop3:0x78
	v_lshl_or_b32 v153, v66, 4, v64
	v_bitop3_b32 v66, v65, v115, 2 bitop3:0x36
	v_lshl_or_b32 v154, v66, 4, v64
	v_bitop3_b32 v66, v65, v115, 4 bitop3:0x36
	v_lshl_or_b32 v155, v66, 4, v64
	v_bitop3_b32 v66, v65, v115, 6 bitop3:0x36
	v_lshl_or_b32 v156, v66, 4, v64
	v_bitop3_b32 v66, v65, v115, 8 bitop3:0x36
	v_lshl_or_b32 v157, v66, 4, v64
	v_bitop3_b32 v66, v65, v115, 10 bitop3:0x36
	v_lshl_or_b32 v158, v66, 4, v64
	v_bitop3_b32 v66, v65, v115, 12 bitop3:0x36
	v_bitop3_b32 v65, v65, v115, 14 bitop3:0x36
	v_bfe_u32 v74, v71, 16, 1
	v_lshl_or_b32 v159, v66, 4, v64
	v_lshl_or_b32 v160, v65, 4, v64
	v_add3_u32 v147, v71, v74, s82
	ds_read2st64_b64 v[74:77], v153 offset0:64 offset1:72
	ds_read2st64_b64 v[100:103], v154 offset0:64 offset1:72
	ds_read2st64_b64 v[116:119], v155 offset0:64 offset1:72
	ds_read2st64_b64 v[120:123], v156 offset0:64 offset1:72
	ds_read2st64_b64 v[124:127], v157 offset0:64 offset1:72
	ds_read2st64_b64 v[128:131], v158 offset0:64 offset1:72
	ds_read2st64_b64 v[132:135], v159 offset0:64 offset1:72
	ds_read2st64_b64 v[136:139], v160 offset0:64 offset1:72
	v_bfe_u32 v72, v67, 16, 1
	v_bfe_u32 v87, v69, 16, 1
	v_add3_u32 v149, v67, v72, s82
	v_add3_u32 v87, v69, v87, s82
	v_perm_b32 v67, v93, v91, s58
	v_perm_b32 v65, v89, v88, s58
	v_perm_b32 v66, v95, v94, s58
	v_perm_b32 v64, v92, v90, s58
	v_pk_mul_f32 v[62:63], v[112:113], v[62:63]
	v_pk_mul_f32 v[60:61], v[108:109], v[60:61]
	s_waitcnt lgkmcnt(7)
	v_mov_b32_e32 v68, v74
	v_mov_b32_e32 v69, v75
	s_waitcnt lgkmcnt(6)
	v_mov_b32_e32 v70, v100
	v_mov_b32_e32 v71, v101
	v_pk_fma_f32 v[30:31], v[110:111], v[30:31], v[62:63]
	v_pk_fma_f32 v[28:29], v[106:107], v[28:29], v[60:61]
	v_perm_b32 v63, v97, v83, s58
	v_perm_b32 v61, v81, v80, s58
	v_perm_b32 v62, v99, v98, s58
	v_perm_b32 v60, v96, v82, s58
	v_mfma_f32_16x16x32_bf16 v[28:31], v[64:67], v[68:71], v[28:31]
	v_mul_f32_e64 v58, v112, v58
	v_mul_f32_e64 v59, v113, v59
	v_pk_mul_f32 v[56:57], v[108:109], v[56:57]
	v_mov_b32_e32 v100, v76
	v_mov_b32_e32 v101, v77
	v_pk_fma_f32 v[2:3], v[110:111], v[2:3], v[58:59]
	v_pk_fma_f32 v[0:1], v[106:107], v[0:1], v[56:57]
	s_waitcnt lgkmcnt(5)
	v_mov_b32_e32 v68, v116
	v_mov_b32_e32 v69, v117
	v_mfma_f32_16x16x32_bf16 v[0:3], v[64:67], v[100:103], v[0:3]
	s_waitcnt lgkmcnt(4)
	v_mov_b32_e32 v70, v120
	v_mov_b32_e32 v71, v121
	v_mov_b32_e32 v120, v118
	v_mov_b32_e32 v121, v119
	v_mfma_f32_16x16x32_bf16 v[28:31], v[60:63], v[68:71], v[28:31]
	v_perm_b32 v71, v141, v140, s58
	v_perm_b32 v69, v79, v78, s58
	v_perm_b32 v70, v145, v144, s58
	v_perm_b32 v68, v143, v142, s58
	v_mfma_f32_16x16x32_bf16 v[0:3], v[60:63], v[120:123], v[0:3]
	s_waitcnt lgkmcnt(3)
	v_mov_b32_e32 v72, v124
	v_mov_b32_e32 v73, v125
	s_waitcnt lgkmcnt(2)
	v_mov_b32_e32 v74, v128
	v_mov_b32_e32 v75, v129
	v_mov_b32_e32 v128, v126
	v_mov_b32_e32 v129, v127
	v_mfma_f32_16x16x32_bf16 v[28:31], v[68:71], v[72:75], v[28:31]
	v_perm_b32 v75, v149, v148, s58
	v_perm_b32 v73, v147, v146, s58
	v_perm_b32 v74, v152, v151, s58
	v_perm_b32 v72, v87, v150, s58
	v_mfma_f32_16x16x32_bf16 v[0:3], v[68:71], v[128:131], v[0:3]
	s_waitcnt lgkmcnt(1)
	v_mov_b32_e32 v78, v132
	v_mov_b32_e32 v79, v133
	s_waitcnt lgkmcnt(0)
; #define SBAR() __builtin_amdgcn_sched_barrier(0)
; __global__ void __launch_bounds__(512) mega(Params p) {
;     ...
;           { const char* vl = shm + 32768 + fr * 256 + (fq & 1) * 8;
; #pragma unroll
;             for (int n2 = 0; n2 < 4; ++n2) { s16x4 lo[2][4], hi[2][4];
; #pragma unroll
;               for (int q2 = 0; q2 < 2; ++q2)
; #pragma unroll
;                 for (int sx = 0; sx < 4; ++sx) { lo[q2][sx] = *(const s16x4*)(vl + (n2 * 2 + q2) * 4096 + ((((sx * 4 + (fq >> 1)) ^ fr) & 15) << 4));
;                   hi[q2][sx] = *(const s16x4*)(vl + (n2 * 2 + q2) * 4096 + ((((sx * 4 + 2 + (fq >> 1)) ^ fr) & 15) << 4)); }
;               SBAR();
; #pragma unroll
;               for (int q2 = 0; q2 < 2; ++q2)
; #pragma unroll
;                 for (int sx = 0; sx < 4; ++sx) { const bf16x8 B = {lo[q2][sx][0], lo[q2][sx][1], lo[q2][sx][2], lo[q2][sx][3], hi[q2][sx][0], hi[q2][sx][1], hi[q2][sx][2], hi[q2][sx][3]};
;                   o[n2 * 2 + q2] = __builtin_amdgcn_mfma_f32_16x16x32_bf16(pf[sx], B, o[n2 * 2 + q2], 0, 0, 0); }
;               SBAR(); } }
	v_mov_b32_e32 v80, v136
	v_mov_b32_e32 v81, v137
	v_mov_b32_e32 v136, v134
	v_mov_b32_e32 v137, v135
	v_mfma_f32_16x16x32_bf16 v[28:31], v[72:75], v[78:81], v[28:31]
	s_nop 0
	v_mfma_f32_16x16x32_bf16 v[0:3], v[72:75], v[136:139], v[0:3]
	ds_read2st64_b64 v[56:59], v153 offset0:80 offset1:88
	ds_read2st64_b64 v[76:79], v154 offset0:80 offset1:88
	ds_read2st64_b64 v[80:83], v155 offset0:80 offset1:88
	ds_read2st64_b64 v[88:91], v156 offset0:80 offset1:88
	ds_read2st64_b64 v[92:95], v157 offset0:80 offset1:88
	ds_read2st64_b64 v[96:99], v158 offset0:80 offset1:88
	ds_read2st64_b64 v[100:103], v159 offset0:80 offset1:88
	ds_read2st64_b64 v[116:119], v160 offset0:80 offset1:88
	v_pk_mul_f32 v[54:55], v[112:113], v[54:55]
	v_pk_mul_f32 v[52:53], v[108:109], v[52:53]
	v_pk_mul_f32 v[50:51], v[112:113], v[50:51]
	v_pk_mul_f32 v[48:49], v[108:109], v[48:49]
	s_waitcnt lgkmcnt(7)
	v_mov_b32_e32 v120, v56
	v_mov_b32_e32 v121, v57
	s_waitcnt lgkmcnt(6)
	v_mov_b32_e32 v122, v76
	v_mov_b32_e32 v123, v77
	v_pk_fma_f32 v[6:7], v[110:111], v[6:7], v[54:55]
	v_pk_fma_f32 v[4:5], v[106:107], v[4:5], v[52:53]
	v_mov_b32_e32 v76, v58
	v_mov_b32_e32 v77, v59
	v_pk_fma_f32 v[10:11], v[110:111], v[10:11], v[50:51]
	v_pk_fma_f32 v[8:9], v[106:107], v[8:9], v[48:49]
	v_mfma_f32_16x16x32_bf16 v[4:7], v[64:67], v[120:123], v[4:7]
	s_waitcnt lgkmcnt(5)
	v_mov_b32_e32 v52, v80
	v_mov_b32_e32 v53, v81
	s_waitcnt lgkmcnt(4)
	v_mov_b32_e32 v54, v88
	v_mfma_f32_16x16x32_bf16 v[8:11], v[64:67], v[76:79], v[8:11]
	v_mov_b32_e32 v55, v89
	v_mov_b32_e32 v88, v82
	v_mov_b32_e32 v89, v83
	v_mfma_f32_16x16x32_bf16 v[4:7], v[60:63], v[52:55], v[4:7]
	s_waitcnt lgkmcnt(3)
	v_mov_b32_e32 v52, v92
	v_mov_b32_e32 v53, v93
	s_waitcnt lgkmcnt(2)
	v_mov_b32_e32 v54, v96
	v_mfma_f32_16x16x32_bf16 v[8:11], v[60:63], v[88:91], v[8:11]
	v_mov_b32_e32 v55, v97
	v_mov_b32_e32 v96, v94
	v_mov_b32_e32 v97, v95
	v_mfma_f32_16x16x32_bf16 v[4:7], v[68:71], v[52:55], v[4:7]
	s_waitcnt lgkmcnt(1)
	v_mov_b32_e32 v52, v100
	v_mov_b32_e32 v53, v101
	s_waitcnt lgkmcnt(0)
	v_mov_b32_e32 v54, v116
	v_mfma_f32_16x16x32_bf16 v[8:11], v[68:71], v[96:99], v[8:11]
	v_mov_b32_e32 v55, v117
	v_mov_b32_e32 v116, v102
	v_mov_b32_e32 v117, v103
	v_mfma_f32_16x16x32_bf16 v[4:7], v[72:75], v[52:55], v[4:7]
	s_nop 0
	v_mfma_f32_16x16x32_bf16 v[8:11], v[72:75], v[116:119], v[8:11]
	ds_read2st64_b64 v[48:51], v153 offset0:96 offset1:104
	ds_read2st64_b64 v[52:55], v154 offset0:96 offset1:104
	ds_read2st64_b64 v[56:59], v155 offset0:96 offset1:104
	ds_read2st64_b64 v[76:79], v156 offset0:96 offset1:104
	ds_read2st64_b64 v[80:83], v157 offset0:96 offset1:104
	ds_read2st64_b64 v[88:91], v158 offset0:96 offset1:104
	ds_read2st64_b64 v[92:95], v159 offset0:96 offset1:104
	ds_read2st64_b64 v[96:99], v160 offset0:96 offset1:104
	v_pk_mul_f32 v[46:47], v[112:113], v[46:47]
	v_pk_mul_f32 v[44:45], v[108:109], v[44:45]
	v_pk_mul_f32 v[42:43], v[112:113], v[42:43]
	v_pk_mul_f32 v[40:41], v[108:109], v[40:41]
	s_waitcnt lgkmcnt(7)
	v_mov_b32_e32 v100, v48
	v_mov_b32_e32 v101, v49
	s_waitcnt lgkmcnt(6)
	v_mov_b32_e32 v102, v52
	v_mov_b32_e32 v103, v53
	v_pk_fma_f32 v[14:15], v[110:111], v[14:15], v[46:47]
	v_pk_fma_f32 v[12:13], v[106:107], v[12:13], v[44:45]
	v_mov_b32_e32 v52, v50
	v_mov_b32_e32 v53, v51
	v_pk_fma_f32 v[18:19], v[110:111], v[18:19], v[42:43]
	v_pk_fma_f32 v[16:17], v[106:107], v[16:17], v[40:41]
	v_mfma_f32_16x16x32_bf16 v[12:15], v[64:67], v[100:103], v[12:15]
	s_waitcnt lgkmcnt(5)
	v_mov_b32_e32 v44, v56
	v_mov_b32_e32 v45, v57
	s_waitcnt lgkmcnt(4)
	v_mov_b32_e32 v46, v76
	v_mfma_f32_16x16x32_bf16 v[16:19], v[64:67], v[52:55], v[16:19]
	v_mov_b32_e32 v47, v77
	v_mov_b32_e32 v76, v58
	v_mov_b32_e32 v77, v59
	v_mfma_f32_16x16x32_bf16 v[12:15], v[60:63], v[44:47], v[12:15]
	s_waitcnt lgkmcnt(3)
	v_mov_b32_e32 v44, v80
	v_mov_b32_e32 v45, v81
	s_waitcnt lgkmcnt(2)
	v_mov_b32_e32 v46, v88
	v_mfma_f32_16x16x32_bf16 v[16:19], v[60:63], v[76:79], v[16:19]
	v_mov_b32_e32 v47, v89
	v_mov_b32_e32 v88, v82
	v_mov_b32_e32 v89, v83
	v_mfma_f32_16x16x32_bf16 v[12:15], v[68:71], v[44:47], v[12:15]
	s_waitcnt lgkmcnt(1)
	v_mov_b32_e32 v44, v92
	v_mov_b32_e32 v45, v93
	s_waitcnt lgkmcnt(0)
	v_mov_b32_e32 v46, v96
	v_mfma_f32_16x16x32_bf16 v[16:19], v[68:71], v[88:91], v[16:19]
	v_mov_b32_e32 v47, v97
	v_mov_b32_e32 v96, v94
	v_mov_b32_e32 v97, v95
	v_mfma_f32_16x16x32_bf16 v[12:15], v[72:75], v[44:47], v[12:15]
	s_nop 0
	v_mfma_f32_16x16x32_bf16 v[16:19], v[72:75], v[96:99], v[16:19]
	ds_read2st64_b64 v[40:43], v153 offset0:112 offset1:120
	ds_read2st64_b64 v[44:47], v154 offset0:112 offset1:120
	ds_read2st64_b64 v[48:51], v155 offset0:112 offset1:120
	ds_read2st64_b64 v[52:55], v156 offset0:112 offset1:120
	ds_read2st64_b64 v[56:59], v157 offset0:112 offset1:120
	ds_read2st64_b64 v[76:79], v158 offset0:112 offset1:120
	ds_read2st64_b64 v[80:83], v159 offset0:112 offset1:120
	ds_read2st64_b64 v[88:91], v160 offset0:112 offset1:120
	v_pk_mul_f32 v[38:39], v[112:113], v[38:39]
	v_pk_mul_f32 v[36:37], v[108:109], v[36:37]
	v_pk_mul_f32 v[34:35], v[112:113], v[34:35]
	v_pk_mul_f32 v[32:33], v[108:109], v[32:33]
	s_waitcnt lgkmcnt(7)
	v_mov_b32_e32 v92, v40
	v_mov_b32_e32 v93, v41
	s_waitcnt lgkmcnt(6)
	v_mov_b32_e32 v94, v44
	v_mov_b32_e32 v95, v45
	v_pk_fma_f32 v[22:23], v[110:111], v[22:23], v[38:39]
	v_pk_fma_f32 v[20:21], v[106:107], v[20:21], v[36:37]
	v_mov_b32_e32 v44, v42
	v_mov_b32_e32 v45, v43
	v_pk_fma_f32 v[26:27], v[110:111], v[26:27], v[34:35]
	v_pk_fma_f32 v[24:25], v[106:107], v[24:25], v[32:33]
	v_mfma_f32_16x16x32_bf16 v[20:23], v[64:67], v[92:95], v[20:23]
	s_waitcnt lgkmcnt(5)
; __global__ void __launch_bounds__(512) mega(Params p) {
;     ...
;           float gw[8];
; #pragma unroll
;           for (int ne = 0; ne < 8; ++ne) gw[ne] = gn_w[head * 128 + ne * 16 + fr];
; #pragma unroll
;           for (int j = 0; j < 4; ++j) { float s1 = 0;
; #pragma unroll
;             for (int ne = 0; ne < 8; ++ne) s1 += o[ne][j];
;             const float mean = red16(s1) * (1.f / 128.f); float s2 = 0;
; #pragma unroll
;             for (int ne = 0; ne < 8; ++ne) { const float dd = o[ne][j] - mean; s2 += dd * dd; }
;             const float rstd = 1.f / sqrtf(red16(s2) * (1.f / 128.f) + LN_EPS);
	v_mov_b32_e32 v36, v48
	v_mov_b32_e32 v37, v49
	s_waitcnt lgkmcnt(4)
	v_mov_b32_e32 v38, v52
	v_mfma_f32_16x16x32_bf16 v[24:27], v[64:67], v[44:47], v[24:27]
	v_mov_b32_e32 v39, v53
	v_mov_b32_e32 v52, v50
	v_mov_b32_e32 v53, v51
	v_mfma_f32_16x16x32_bf16 v[20:23], v[60:63], v[36:39], v[20:23]
	s_waitcnt lgkmcnt(3)
	v_mov_b32_e32 v36, v56
	v_mov_b32_e32 v37, v57
	s_waitcnt lgkmcnt(2)
	v_mov_b32_e32 v38, v76
	v_mfma_f32_16x16x32_bf16 v[24:27], v[60:63], v[52:55], v[24:27]
	v_mov_b32_e32 v39, v77
	v_mov_b32_e32 v76, v58
	v_mov_b32_e32 v77, v59
	v_mfma_f32_16x16x32_bf16 v[20:23], v[68:71], v[36:39], v[20:23]
	s_waitcnt lgkmcnt(1)
	v_mov_b32_e32 v36, v80
	v_mov_b32_e32 v37, v81
	s_waitcnt lgkmcnt(0)
	v_mov_b32_e32 v38, v88
	v_mfma_f32_16x16x32_bf16 v[24:27], v[68:71], v[76:79], v[24:27]
	v_mov_b32_e32 v39, v89
	v_mov_b32_e32 v88, v82
	v_mov_b32_e32 v89, v83
	v_mfma_f32_16x16x32_bf16 v[20:23], v[72:75], v[36:39], v[20:23]
	s_nop 0
	v_mfma_f32_16x16x32_bf16 v[24:27], v[72:75], v[88:91], v[24:27]
	s_mov_b64 s[2:3], s[0:1]
	s_load_dwordx2 s[4:5], s[2:3], 0x50
	s_lshl_b64 s[2:3], s[54:55], 2
	v_lshlrev_b32_e32 v32, 2, v115
	v_lshl_or_b32 v32, s17, 9, v32
	v_or_b32_e32 v104, s7, v104
	s_waitcnt lgkmcnt(0)
	s_add_u32 s4, s4, s2
	s_addc_u32 s5, s5, s3
	global_load_dword v43, v32, s[4:5]
	s_mov_b64 s[4:5], s[0:1]
	s_load_dwordx2 s[4:5], s[4:5], 0x50
	v_lshlrev_b32_e32 v176, 1, v115
	s_waitcnt lgkmcnt(0)
	s_add_u32 s4, s4, s2
	s_addc_u32 s5, s5, s3
	global_load_dword v36, v32, s[4:5] offset:64
	s_mov_b64 s[4:5], s[0:1]
	s_load_dwordx2 s[4:5], s[4:5], 0x50
	s_waitcnt lgkmcnt(0)
	s_add_u32 s4, s4, s2
	s_addc_u32 s5, s5, s3
	global_load_dword v37, v32, s[4:5] offset:128
	s_mov_b64 s[4:5], s[0:1]
	s_load_dwordx2 s[4:5], s[4:5], 0x50
	s_waitcnt lgkmcnt(0)
	s_add_u32 s4, s4, s2
	s_addc_u32 s5, s5, s3
	global_load_dword v38, v32, s[4:5] offset:192
	s_mov_b64 s[4:5], s[0:1]
	s_load_dwordx2 s[4:5], s[4:5], 0x50
	s_waitcnt lgkmcnt(0)
	s_add_u32 s4, s4, s2
	s_addc_u32 s5, s5, s3
	global_load_dword v39, v32, s[4:5] offset:256
	s_mov_b64 s[4:5], s[0:1]
	s_load_dwordx2 s[4:5], s[4:5], 0x50
	s_waitcnt lgkmcnt(0)
	s_add_u32 s4, s4, s2
	s_addc_u32 s5, s5, s3
	global_load_dword v41, v32, s[4:5] offset:320
	s_mov_b64 s[4:5], s[0:1]
	s_load_dwordx2 s[4:5], s[4:5], 0x50
	s_waitcnt lgkmcnt(0)
	s_add_u32 s4, s4, s2
	s_addc_u32 s5, s5, s3
	global_load_dword v40, v32, s[4:5] offset:384
	s_mov_b64 s[4:5], s[0:1]
	s_load_dwordx2 s[4:5], s[4:5], 0x50
	s_waitcnt lgkmcnt(0)
	s_add_u32 s2, s4, s2
	s_addc_u32 s3, s5, s3
	global_load_dword v42, v32, s[2:3] offset:448
	v_add_f32_e32 v32, 0, v28
	v_add_f32_e32 v32, v32, v0
	v_add_f32_e32 v32, v32, v4
	v_add_f32_e32 v32, v32, v8
	s_mov_b32 s2, -1
	v_add_f32_e32 v32, v32, v12
	v_add_f32_e32 v32, v32, v16
	v_mbcnt_lo_u32_b32 v33, s2, 0
	v_mbcnt_hi_u32_b32 v33, s2, v33
	v_add_f32_e32 v32, v32, v20
	v_lshlrev_b32_e32 v33, 2, v33
	v_add_f32_e32 v32, v32, v24
	v_xor_b32_e32 v34, 4, v33
	ds_bpermute_b32 v34, v34, v32
	s_mov_b32 s2, -1
	s_add_i32 s16, s16, s28
	s_add_u32 s8, s8, s72
	s_waitcnt lgkmcnt(0)
	v_add_f32_e32 v32, v32, v34
	v_xor_b32_e32 v34, 8, v33
	ds_bpermute_b32 v34, v34, v32
	s_addc_u32 s9, s9, s73
	s_add_i32 s6, s6, s59
	s_cmpk_gt_i32 s16, 0x3ff
	s_waitcnt lgkmcnt(0)
	v_add_f32_e32 v32, v32, v34
	v_xor_b32_e32 v34, 16, v33
	ds_bpermute_b32 v34, v34, v32
	v_xor_b32_e32 v33, 32, v33
	s_waitcnt lgkmcnt(0)
	v_add_f32_e32 v32, v32, v34
	ds_bpermute_b32 v33, v33, v32
	s_waitcnt lgkmcnt(0)
	v_add_f32_e32 v32, v32, v33
	v_fmamk_f32 v45, v32, 0xbc000000, v0
	v_fmamk_f32 v50, v32, 0xbc000000, v28
	v_mul_f32_e32 v33, v45, v45
	v_fmac_f32_e32 v33, v50, v50
	v_fmamk_f32 v44, v32, 0xbc000000, v4
	v_fmac_f32_e32 v33, v44, v44
	v_fmamk_f32 v28, v32, 0xbc000000, v8
	v_fmac_f32_e32 v33, v28, v28
	v_fmamk_f32 v12, v32, 0xbc000000, v12
	v_fmac_f32_e32 v33, v12, v12
	v_fmamk_f32 v8, v32, 0xbc000000, v16
	v_mbcnt_lo_u32_b32 v16, s2, 0
	v_fmac_f32_e32 v33, v8, v8
	v_fmamk_f32 v4, v32, 0xbc000000, v20
	v_mbcnt_hi_u32_b32 v16, s2, v16
	v_fmac_f32_e32 v33, v4, v4
	v_fmamk_f32 v0, v32, 0xbc000000, v24
	v_lshlrev_b32_e32 v16, 2, v16
	v_fmac_f32_e32 v33, v0, v0
	v_xor_b32_e32 v20, 4, v16
	ds_bpermute_b32 v20, v20, v33
	v_xor_b32_e32 v24, 8, v16
	s_waitcnt lgkmcnt(0)
	v_add_f32_e32 v20, v33, v20
	ds_bpermute_b32 v24, v24, v20
	s_waitcnt lgkmcnt(0)
	v_add_f32_e32 v20, v20, v24
	v_xor_b32_e32 v24, 16, v16
	ds_bpermute_b32 v24, v24, v20
	v_xor_b32_e32 v16, 32, v16
	s_waitcnt lgkmcnt(0)
	v_add_f32_e32 v20, v20, v24
	ds_bpermute_b32 v16, v16, v20
	s_waitcnt lgkmcnt(0)
	v_add_f32_e32 v16, v20, v16
	v_fmamk_f32 v16, v16, 0x3c000000, v183
	v_cmp_gt_f32_e32 vcc, s30, v16
	v_mul_f32_e32 v20, 0x4f800000, v16
	s_nop 0
	v_cndmask_b32_e32 v16, v16, v20, vcc
	v_sqrt_f32_e32 v20, v16
	s_nop 0
	v_add_u32_e32 v24, -1, v20
	v_fma_f32 v32, -v24, v20, v16
	v_cmp_ge_f32_e64 s[4:5], 0, v32
	v_add_u32_e32 v32, 1, v20
	s_nop 0
	v_cndmask_b32_e64 v24, v20, v24, s[4:5]
	v_fma_f32 v20, -v32, v20, v16
	v_cmp_lt_f32_e64 s[4:5], 0, v20
	s_nop 1
	v_cndmask_b32_e64 v20, v24, v32, s[4:5]
	v_mul_f32_e32 v24, 0x37800000, v20
	v_cndmask_b32_e32 v20, v20, v24, vcc
	v_cmp_class_f32_e32 vcc, v16, v222
	s_nop 1
	v_cndmask_b32_e32 v16, v20, v16, vcc
	s_mov_b64 s[2:3], s[0:1]
	s_load_dwordx2 s[2:3], s[2:3], 0xe8
	v_lshlrev_b64 v[34:35], 11, v[104:105]
	v_rcp_f32_e32 v24, v16
	s_nop 0
	v_fma_f32 v20, -v16, v24, 1.0
	v_fma_f32 v20, v20, v24, v24
	s_waitcnt lgkmcnt(0)
; DEVFI float bf2f(bfraw h) { return __uint_as_float(((unsigned)h) << 16); }
; DEVFI bfraw f2bf(float x) { unsigned u = __float_as_uint(x); u += 0x7fffu + ((u >> 16) & 1u); return (bfraw)(u >> 16); }
; #define RG ((bfraw*)(kargs()->ws + O_RG))
; #define RO ((bfraw*)(kargs()->ws + O_RO))
; __global__ void __launch_bounds__(512) mega(Params p) {
;     ...
;           for (int j = 0; j < 4; ++j) { float s1 = 0;
; #pragma unroll
;             for (int ne = 0; ne < 8; ++ne) s1 += o[ne][j];
;             const float mean = red16(s1) * (1.f / 128.f); float s2 = 0;
; #pragma unroll
;             for (int ne = 0; ne < 8; ++ne) { const float dd = o[ne][j] - mean; s2 += dd * dd; }
;             const float rstd = 1.f / sqrtf(red16(s2) * (1.f / 128.f) + LN_EPS);
;             const long tok = tok0 + w * 16 + fq * 4 + j;
;             const bfraw* gp = RG + tok * 1024 + head * 128 + fr; bfraw* op = RO + tok * 1024 + head * 128 + fr;
; #pragma unroll
;             for (int ne = 0; ne < 8; ++ne) op[ne * 16] = f2bf((o[ne][j] - mean) * rstd * gw[ne] * bf2f(gp[ne * 16])); }
	v_lshl_add_u64 v[32:33], s[2:3], 0, v[34:35]
	v_lshl_add_u64 v[32:33], v[32:33], 0, s[12:13]
	v_lshl_add_u64 v[46:47], v[32:33], 0, v[176:177]
	v_lshl_add_u64 v[32:33], v[46:47], 0, s[42:43]
	v_add_co_u32_e32 v46, vcc, s68, v46
	s_mov_b64 s[2:3], s[0:1]
	s_nop 0
	v_addc_co_u32_e32 v47, vcc, 0, v47, vcc
	global_load_ushort v24, v[46:47], off
	global_load_ushort v184, v[32:33], off offset:32
	global_load_ushort v185, v[32:33], off offset:64
	global_load_ushort v186, v[32:33], off offset:96
	global_load_ushort v187, v[32:33], off offset:128
	global_load_ushort v188, v[32:33], off offset:160
	global_load_ushort v189, v[32:33], off offset:192
	global_load_ushort v190, v[32:33], off offset:224
	s_load_dwordx2 s[2:3], s[2:3], 0xe8
	v_div_fixup_f32 v16, v20, v16, 1.0
	v_mul_f32_e32 v20, v16, v50
	s_waitcnt vmcnt(8)
	v_mul_f32_e32 v20, v20, v43
	v_mul_f32_e32 v12, v16, v12
	s_waitcnt lgkmcnt(0)
	v_lshl_add_u64 v[34:35], s[2:3], 0, v[34:35]
	v_lshl_add_u64 v[34:35], v[34:35], 0, s[12:13]
	v_lshl_add_u64 v[48:49], v[34:35], 0, v[176:177]
	v_add_co_u32_e32 v46, vcc, s69, v48
	v_lshl_add_u64 v[34:35], v[48:49], 0, s[50:51]
	s_nop 0
	v_addc_co_u32_e32 v47, vcc, 0, v49, vcc
	s_waitcnt vmcnt(4)
	v_mul_f32_e32 v12, v12, v39
	v_mul_f32_e32 v8, v16, v8
	s_waitcnt vmcnt(3)
	v_mul_f32_e32 v8, v8, v41
	v_mul_f32_e32 v4, v16, v4
	s_waitcnt vmcnt(2)
	v_mul_f32_e32 v4, v4, v40
	v_mul_f32_e32 v0, v16, v0
	s_waitcnt vmcnt(1)
	v_mul_f32_e32 v0, v0, v42
	s_mov_b32 s2, -1
	v_or_b32_e32 v104, s7, v86
	s_waitcnt vmcnt(0)
	v_lshlrev_b32_e32 v24, 16, v24
	v_mul_f32_e32 v20, v20, v24
	v_bfe_u32 v24, v20, 16, 1
	v_add3_u32 v20, v20, v24, s82
	global_store_short_d16_hi v[46:47], v20, off
	v_mul_f32_e32 v20, v16, v45
	v_mul_f32_e32 v20, v20, v36
	v_lshlrev_b32_e32 v24, 16, v184
	v_mul_f32_e32 v20, v20, v24
	v_bfe_u32 v24, v20, 16, 1
	v_add3_u32 v20, v20, v24, s82
	global_store_short_d16_hi v[34:35], v20, off offset:32
	v_mul_f32_e32 v20, v16, v44
	v_mul_f32_e32 v20, v20, v37
	v_lshlrev_b32_e32 v24, 16, v185
	v_mul_f32_e32 v20, v20, v24
	v_bfe_u32 v24, v20, 16, 1
	v_add3_u32 v20, v20, v24, s82
	global_store_short_d16_hi v[34:35], v20, off offset:64
	v_mul_f32_e32 v20, v16, v28
	v_mul_f32_e32 v20, v20, v38
	v_lshlrev_b32_e32 v24, 16, v186
	v_mul_f32_e32 v20, v20, v24
	v_bfe_u32 v24, v20, 16, 1
	v_add3_u32 v20, v20, v24, s82
	global_store_short_d16_hi v[34:35], v20, off offset:96
	v_lshlrev_b32_e32 v20, 16, v187
	v_mul_f32_e32 v12, v12, v20
	v_bfe_u32 v20, v12, 16, 1
	v_add3_u32 v12, v12, v20, s82
	global_store_short_d16_hi v[34:35], v12, off offset:128
	v_lshlrev_b32_e32 v12, 16, v188
	v_mul_f32_e32 v8, v8, v12
	v_bfe_u32 v12, v8, 16, 1
	v_add3_u32 v8, v8, v12, s82
	global_store_short_d16_hi v[34:35], v8, off offset:160
	v_lshlrev_b32_e32 v8, 16, v189
	v_mul_f32_e32 v4, v4, v8
	v_bfe_u32 v8, v4, 16, 1
	v_add3_u32 v4, v4, v8, s82
	global_store_short_d16_hi v[34:35], v4, off offset:192
	v_lshlrev_b32_e32 v4, 16, v190
	v_mul_f32_e32 v0, v0, v4
	v_bfe_u32 v4, v0, 16, 1
	v_add3_u32 v0, v0, v4, s82
	global_store_short_d16_hi v[34:35], v0, off offset:224
	v_add_f32_e32 v0, 0, v29
	v_add_f32_e32 v0, v0, v1
	v_add_f32_e32 v0, v0, v5
	v_add_f32_e32 v0, v0, v9
	v_add_f32_e32 v0, v0, v13
	v_add_f32_e32 v0, v0, v17
	v_mbcnt_lo_u32_b32 v4, s2, 0
	v_mbcnt_hi_u32_b32 v4, s2, v4
	v_add_f32_e32 v0, v0, v21
	v_lshlrev_b32_e32 v4, 2, v4
	v_add_f32_e32 v0, v0, v25
	v_xor_b32_e32 v8, 4, v4
	ds_bpermute_b32 v8, v8, v0
	s_mov_b32 s2, -1
	s_waitcnt lgkmcnt(0)
	v_add_f32_e32 v0, v0, v8
	v_xor_b32_e32 v8, 8, v4
	ds_bpermute_b32 v8, v8, v0
	s_waitcnt lgkmcnt(0)
	v_add_f32_e32 v0, v0, v8
	v_xor_b32_e32 v8, 16, v4
	ds_bpermute_b32 v8, v8, v0
	v_xor_b32_e32 v4, 32, v4
	s_waitcnt lgkmcnt(0)
	v_add_f32_e32 v0, v0, v8
	ds_bpermute_b32 v4, v4, v0
	s_waitcnt lgkmcnt(0)
	v_add_f32_e32 v0, v0, v4
	v_fmamk_f32 v24, v0, 0xbc000000, v1
	v_fmamk_f32 v34, v0, 0xbc000000, v29
	v_mul_f32_e32 v1, v24, v24
	v_fmac_f32_e32 v1, v34, v34
	v_fmamk_f32 v20, v0, 0xbc000000, v5
	v_fmac_f32_e32 v1, v20, v20
	v_fmamk_f32 v16, v0, 0xbc000000, v9
	v_fmac_f32_e32 v1, v16, v16
	v_fmamk_f32 v13, v0, 0xbc000000, v13
	v_fmac_f32_e32 v1, v13, v13
	v_fmamk_f32 v12, v0, 0xbc000000, v17
	v_fmamk_f32 v9, v0, 0xbc000000, v21
	v_fmamk_f32 v8, v0, 0xbc000000, v25
	v_mbcnt_lo_u32_b32 v0, s2, 0
	v_fmac_f32_e32 v1, v12, v12
	v_mbcnt_hi_u32_b32 v0, s2, v0
	v_fmac_f32_e32 v1, v9, v9
	v_lshlrev_b32_e32 v0, 2, v0
	v_fmac_f32_e32 v1, v8, v8
	v_xor_b32_e32 v4, 4, v0
	ds_bpermute_b32 v4, v4, v1
	s_waitcnt lgkmcnt(0)
	v_add_f32_e32 v1, v1, v4
	v_xor_b32_e32 v4, 8, v0
	ds_bpermute_b32 v4, v4, v1
	s_waitcnt lgkmcnt(0)
	v_add_f32_e32 v1, v1, v4
	v_xor_b32_e32 v4, 16, v0
	ds_bpermute_b32 v4, v4, v1
	v_xor_b32_e32 v0, 32, v0
	s_waitcnt lgkmcnt(0)
	v_add_f32_e32 v1, v1, v4
	ds_bpermute_b32 v0, v0, v1
	s_waitcnt lgkmcnt(0)
	v_add_f32_e32 v0, v1, v0
	v_fmamk_f32 v0, v0, 0x3c000000, v183
	v_cmp_gt_f32_e32 vcc, s30, v0
	v_mul_f32_e32 v1, 0x4f800000, v0
	s_nop 0
	v_cndmask_b32_e32 v0, v0, v1, vcc
	v_sqrt_f32_e32 v1, v0
	s_nop 0
	v_add_u32_e32 v4, -1, v1
	v_fma_f32 v5, -v4, v1, v0
	v_cmp_ge_f32_e64 s[4:5], 0, v5
	v_add_u32_e32 v5, 1, v1
	s_nop 0
	v_cndmask_b32_e64 v4, v1, v4, s[4:5]
	v_fma_f32 v1, -v5, v1, v0
	v_cmp_lt_f32_e64 s[4:5], 0, v1
	s_nop 1
	v_cndmask_b32_e64 v1, v4, v5, s[4:5]
	v_mul_f32_e32 v4, 0x37800000, v1
	v_cndmask_b32_e32 v1, v1, v4, vcc
	v_cmp_class_f32_e32 vcc, v0, v222
	s_nop 1
	v_cndmask_b32_e32 v0, v1, v0, vcc
	s_mov_b64 s[2:3], s[0:1]
	s_load_dwordx2 s[2:3], s[2:3], 0xe8
	v_rcp_f32_e32 v4, v0
	s_nop 0
	v_fma_f32 v1, -v0, v4, 1.0
	v_fma_f32 v1, v1, v4, v4
	v_lshlrev_b64 v[4:5], 11, v[104:105]
	v_div_fixup_f32 v17, v1, v0, 1.0
	s_waitcnt lgkmcnt(0)
; DEVFI float bf2f(bfraw h) { return __uint_as_float(((unsigned)h) << 16); }
; DEVFI bfraw f2bf(float x) { unsigned u = __float_as_uint(x); u += 0x7fffu + ((u >> 16) & 1u); return (bfraw)(u >> 16); }
; #define RG ((bfraw*)(kargs()->ws + O_RG))
; #define RO ((bfraw*)(kargs()->ws + O_RO))
; __global__ void __launch_bounds__(512) mega(Params p) {
;     ...
;           for (int j = 0; j < 4; ++j) { float s1 = 0;
; #pragma unroll
;             for (int ne = 0; ne < 8; ++ne) s1 += o[ne][j];
;             const float mean = red16(s1) * (1.f / 128.f); float s2 = 0;
; #pragma unroll
;             for (int ne = 0; ne < 8; ++ne) { const float dd = o[ne][j] - mean; s2 += dd * dd; }
;             const float rstd = 1.f / sqrtf(red16(s2) * (1.f / 128.f) + LN_EPS);
;             const long tok = tok0 + w * 16 + fq * 4 + j;
;             const bfraw* gp = RG + tok * 1024 + head * 128 + fr; bfraw* op = RO + tok * 1024 + head * 128 + fr;
; #pragma unroll
;             for (int ne = 0; ne < 8; ++ne) op[ne * 16] = f2bf((o[ne][j] - mean) * rstd * gw[ne] * bf2f(gp[ne * 16])); }
	v_lshl_add_u64 v[0:1], s[2:3], 0, v[4:5]
	v_lshl_add_u64 v[0:1], v[0:1], 0, s[12:13]
	v_lshl_add_u64 v[28:29], v[0:1], 0, v[176:177]
	v_lshl_add_u64 v[0:1], v[28:29], 0, s[42:43]
	v_add_co_u32_e32 v28, vcc, s68, v28
	s_mov_b64 s[2:3], s[0:1]
	s_nop 0
	v_addc_co_u32_e32 v29, vcc, 0, v29, vcc
	global_load_ushort v25, v[28:29], off
	global_load_ushort v184, v[0:1], off offset:32
	global_load_ushort v185, v[0:1], off offset:64
	global_load_ushort v186, v[0:1], off offset:96
	global_load_ushort v187, v[0:1], off offset:128
	global_load_ushort v188, v[0:1], off offset:160
	global_load_ushort v189, v[0:1], off offset:192
	global_load_ushort v190, v[0:1], off offset:224
	s_load_dwordx2 s[2:3], s[2:3], 0xe8
	v_mul_f32_e32 v21, v17, v34
	v_mul_f32_e32 v21, v21, v43
	v_mul_f32_e32 v20, v17, v20
	v_mul_f32_e32 v20, v20, v37
	s_waitcnt lgkmcnt(0)
	v_lshl_add_u64 v[4:5], s[2:3], 0, v[4:5]
	v_lshl_add_u64 v[4:5], v[4:5], 0, s[12:13]
	v_lshl_add_u64 v[32:33], v[4:5], 0, v[176:177]
	v_add_co_u32_e32 v28, vcc, s69, v32
	v_lshl_add_u64 v[4:5], v[32:33], 0, s[50:51]
	s_nop 0
	v_addc_co_u32_e32 v29, vcc, 0, v33, vcc
	v_mul_f32_e32 v16, v17, v16
	v_mul_f32_e32 v16, v16, v38
	v_mul_f32_e32 v13, v17, v13
	v_mul_f32_e32 v13, v13, v39
	v_mul_f32_e32 v12, v17, v12
	v_mul_f32_e32 v12, v12, v41
	v_mul_f32_e32 v9, v17, v9
	v_mul_f32_e32 v9, v9, v40
	v_mul_f32_e32 v8, v17, v8
	v_mul_f32_e32 v8, v8, v42
	s_mov_b32 s2, -1
	v_or_b32_e32 v104, s7, v85
	s_waitcnt vmcnt(0)
	v_lshlrev_b32_e32 v25, 16, v25
	v_mul_f32_e32 v21, v21, v25
	v_bfe_u32 v25, v21, 16, 1
	v_add3_u32 v21, v21, v25, s82
	global_store_short_d16_hi v[28:29], v21, off
	v_mul_f32_e32 v21, v17, v24
	v_mul_f32_e32 v21, v21, v36
	v_lshlrev_b32_e32 v24, 16, v184
	v_mul_f32_e32 v21, v21, v24
	v_bfe_u32 v24, v21, 16, 1
	v_add3_u32 v21, v21, v24, s82
	global_store_short_d16_hi v[4:5], v21, off offset:32
	v_lshlrev_b32_e32 v21, 16, v185
	v_mul_f32_e32 v20, v20, v21
	v_bfe_u32 v21, v20, 16, 1
	v_add3_u32 v20, v20, v21, s82
	global_store_short_d16_hi v[4:5], v20, off offset:64
	v_lshlrev_b32_e32 v20, 16, v186
	v_mul_f32_e32 v16, v16, v20
	v_bfe_u32 v20, v16, 16, 1
	v_add3_u32 v16, v16, v20, s82
	global_store_short_d16_hi v[4:5], v16, off offset:96
	v_lshlrev_b32_e32 v16, 16, v187
	v_mul_f32_e32 v13, v13, v16
	v_bfe_u32 v16, v13, 16, 1
	v_add3_u32 v13, v13, v16, s82
	global_store_short_d16_hi v[4:5], v13, off offset:128
	v_lshlrev_b32_e32 v13, 16, v188
	v_mul_f32_e32 v12, v12, v13
	v_bfe_u32 v13, v12, 16, 1
	v_add3_u32 v12, v12, v13, s82
	global_store_short_d16_hi v[4:5], v12, off offset:160
	v_lshlrev_b32_e32 v12, 16, v189
	v_mul_f32_e32 v9, v9, v12
	v_bfe_u32 v12, v9, 16, 1
	v_add3_u32 v9, v9, v12, s82
	global_store_short_d16_hi v[4:5], v9, off offset:192
	v_lshlrev_b32_e32 v0, 16, v190
	v_mul_f32_e32 v0, v8, v0
	v_bfe_u32 v1, v0, 16, 1
	v_add3_u32 v0, v0, v1, s82
	global_store_short_d16_hi v[4:5], v0, off offset:224
	v_add_f32_e32 v0, 0, v30
	v_add_f32_e32 v0, v0, v2
	v_add_f32_e32 v0, v0, v6
	v_add_f32_e32 v0, v0, v10
	v_add_f32_e32 v0, v0, v14
	v_add_f32_e32 v0, v0, v18
	v_mbcnt_lo_u32_b32 v1, s2, 0
	v_mbcnt_hi_u32_b32 v1, s2, v1
	v_add_f32_e32 v0, v0, v22
	v_lshlrev_b32_e32 v1, 2, v1
	v_add_f32_e32 v0, v0, v26
	v_xor_b32_e32 v4, 4, v1
	ds_bpermute_b32 v4, v4, v0
	s_mov_b32 s2, -1
	s_waitcnt lgkmcnt(0)
	v_add_f32_e32 v0, v0, v4
	v_xor_b32_e32 v4, 8, v1
	ds_bpermute_b32 v4, v4, v0
	s_waitcnt lgkmcnt(0)
	v_add_f32_e32 v0, v0, v4
	v_xor_b32_e32 v4, 16, v1
	ds_bpermute_b32 v4, v4, v0
	v_xor_b32_e32 v1, 32, v1
	s_waitcnt lgkmcnt(0)
	v_add_f32_e32 v0, v0, v4
	ds_bpermute_b32 v1, v1, v0
	s_waitcnt lgkmcnt(0)
	v_add_f32_e32 v0, v0, v1
	v_fmamk_f32 v13, v0, 0xbc000000, v2
	v_fmamk_f32 v24, v0, 0xbc000000, v30
	v_mul_f32_e32 v1, v13, v13
	v_fmac_f32_e32 v1, v24, v24
	v_fmamk_f32 v12, v0, 0xbc000000, v6
	v_fmac_f32_e32 v1, v12, v12
	v_fmamk_f32 v10, v0, 0xbc000000, v10
	v_fmac_f32_e32 v1, v10, v10
	v_fmamk_f32 v9, v0, 0xbc000000, v14
	v_fmac_f32_e32 v1, v9, v9
	v_fmamk_f32 v8, v0, 0xbc000000, v18
	v_fmamk_f32 v6, v0, 0xbc000000, v22
	v_fmamk_f32 v2, v0, 0xbc000000, v26
	v_mbcnt_lo_u32_b32 v0, s2, 0
	v_fmac_f32_e32 v1, v8, v8
	v_mbcnt_hi_u32_b32 v0, s2, v0
	v_fmac_f32_e32 v1, v6, v6
	v_lshlrev_b32_e32 v0, 2, v0
	v_fmac_f32_e32 v1, v2, v2
	v_xor_b32_e32 v4, 4, v0
	ds_bpermute_b32 v4, v4, v1
	s_waitcnt lgkmcnt(0)
	v_add_f32_e32 v1, v1, v4
	v_xor_b32_e32 v4, 8, v0
	ds_bpermute_b32 v4, v4, v1
	s_waitcnt lgkmcnt(0)
	v_add_f32_e32 v1, v1, v4
	v_xor_b32_e32 v4, 16, v0
	ds_bpermute_b32 v4, v4, v1
	v_xor_b32_e32 v0, 32, v0
	s_waitcnt lgkmcnt(0)
	v_add_f32_e32 v1, v1, v4
	ds_bpermute_b32 v0, v0, v1
	s_waitcnt lgkmcnt(0)
	v_add_f32_e32 v0, v1, v0
	v_fmamk_f32 v0, v0, 0x3c000000, v183
	v_cmp_gt_f32_e32 vcc, s30, v0
	v_mul_f32_e32 v1, 0x4f800000, v0
	s_nop 0
	v_cndmask_b32_e32 v0, v0, v1, vcc
	v_sqrt_f32_e32 v1, v0
	s_nop 0
	v_add_u32_e32 v4, -1, v1
	v_fma_f32 v5, -v4, v1, v0
	v_cmp_ge_f32_e64 s[4:5], 0, v5
	v_add_u32_e32 v5, 1, v1
	s_nop 0
	v_cndmask_b32_e64 v4, v1, v4, s[4:5]
	v_fma_f32 v1, -v5, v1, v0
	v_cmp_lt_f32_e64 s[4:5], 0, v1
	s_nop 1
	v_cndmask_b32_e64 v1, v4, v5, s[4:5]
	v_mul_f32_e32 v4, 0x37800000, v1
	v_cndmask_b32_e32 v1, v1, v4, vcc
	v_cmp_class_f32_e32 vcc, v0, v222
	s_nop 1
	v_cndmask_b32_e32 v0, v1, v0, vcc
	s_mov_b64 s[2:3], s[0:1]
	s_load_dwordx2 s[2:3], s[2:3], 0xe8
	v_rcp_f32_e32 v4, v0
	s_nop 0
	v_fma_f32 v1, -v0, v4, 1.0
	v_fma_f32 v1, v1, v4, v4
	v_lshlrev_b64 v[4:5], 11, v[104:105]
	v_div_fixup_f32 v14, v1, v0, 1.0
	s_waitcnt lgkmcnt(0)
; DEVFI float bf2f(bfraw h) { return __uint_as_float(((unsigned)h) << 16); }
; DEVFI bfraw f2bf(float x) { unsigned u = __float_as_uint(x); u += 0x7fffu + ((u >> 16) & 1u); return (bfraw)(u >> 16); }
; #define RG ((bfraw*)(kargs()->ws + O_RG))
; #define RO ((bfraw*)(kargs()->ws + O_RO))
; __global__ void __launch_bounds__(512) mega(Params p) {
;     ...
;           for (int j = 0; j < 4; ++j) { float s1 = 0;
; #pragma unroll
;             for (int ne = 0; ne < 8; ++ne) s1 += o[ne][j];
;             const float mean = red16(s1) * (1.f / 128.f); float s2 = 0;
; #pragma unroll
;             for (int ne = 0; ne < 8; ++ne) { const float dd = o[ne][j] - mean; s2 += dd * dd; }
;             const float rstd = 1.f / sqrtf(red16(s2) * (1.f / 128.f) + LN_EPS);
;             const long tok = tok0 + w * 16 + fq * 4 + j;
;             const bfraw* gp = RG + tok * 1024 + head * 128 + fr; bfraw* op = RO + tok * 1024 + head * 128 + fr;
; #pragma unroll
;             for (int ne = 0; ne < 8; ++ne) op[ne * 16] = f2bf((o[ne][j] - mean) * rstd * gw[ne] * bf2f(gp[ne * 16])); }
	v_lshl_add_u64 v[0:1], s[2:3], 0, v[4:5]
	v_lshl_add_u64 v[0:1], v[0:1], 0, s[12:13]
	v_lshl_add_u64 v[16:17], v[0:1], 0, v[176:177]
	v_lshl_add_u64 v[0:1], v[16:17], 0, s[42:43]
	v_add_co_u32_e32 v16, vcc, s68, v16
	s_mov_b64 s[2:3], s[0:1]
	s_nop 0
	v_addc_co_u32_e32 v17, vcc, 0, v17, vcc
	global_load_ushort v16, v[16:17], off
	global_load_ushort v184, v[0:1], off offset:32
	global_load_ushort v185, v[0:1], off offset:64
	global_load_ushort v186, v[0:1], off offset:96
	global_load_ushort v187, v[0:1], off offset:128
	global_load_ushort v188, v[0:1], off offset:160
	global_load_ushort v189, v[0:1], off offset:192
	global_load_ushort v190, v[0:1], off offset:224
	s_load_dwordx2 s[2:3], s[2:3], 0xe8
	v_mul_f32_e32 v18, v14, v24
	v_mul_f32_e32 v18, v18, v43
	v_mul_f32_e32 v13, v14, v13
	v_mul_f32_e32 v13, v13, v36
	s_waitcnt lgkmcnt(0)
	v_lshl_add_u64 v[4:5], s[2:3], 0, v[4:5]
	v_lshl_add_u64 v[4:5], v[4:5], 0, s[12:13]
	v_lshl_add_u64 v[20:21], v[4:5], 0, v[176:177]
	v_lshl_add_u64 v[4:5], v[20:21], 0, s[50:51]
	v_mul_f32_e32 v12, v14, v12
	v_mul_f32_e32 v12, v12, v37
	v_mul_f32_e32 v10, v14, v10
	v_mul_f32_e32 v10, v10, v38
	v_mul_f32_e32 v9, v14, v9
	v_mul_f32_e32 v9, v9, v39
	v_mul_f32_e32 v8, v14, v8
	v_mul_f32_e32 v8, v8, v41
	v_mul_f32_e32 v6, v14, v6
	v_mul_f32_e32 v6, v6, v40
	v_mul_f32_e32 v2, v14, v2
	v_mul_f32_e32 v2, v2, v42
	s_mov_b32 s2, -1
	v_or_b32_e32 v104, s7, v84
	s_waitcnt vmcnt(0)
	v_lshlrev_b32_e32 v16, 16, v16
	v_mul_f32_e32 v16, v18, v16
	v_bfe_u32 v17, v16, 16, 1
	v_add3_u32 v18, v16, v17, s82
	v_add_co_u32_e32 v16, vcc, s69, v20
	s_nop 1
	v_addc_co_u32_e32 v17, vcc, 0, v21, vcc
	global_store_short_d16_hi v[16:17], v18, off
	v_lshlrev_b32_e32 v16, 16, v184
	v_mul_f32_e32 v13, v13, v16
	v_bfe_u32 v16, v13, 16, 1
	v_add3_u32 v13, v13, v16, s82
	global_store_short_d16_hi v[4:5], v13, off offset:32
	v_lshlrev_b32_e32 v13, 16, v185
	v_mul_f32_e32 v12, v12, v13
	v_bfe_u32 v13, v12, 16, 1
	v_add3_u32 v12, v12, v13, s82
	global_store_short_d16_hi v[4:5], v12, off offset:64
	v_lshlrev_b32_e32 v12, 16, v186
	v_mul_f32_e32 v10, v10, v12
	v_bfe_u32 v12, v10, 16, 1
	v_add3_u32 v10, v10, v12, s82
	global_store_short_d16_hi v[4:5], v10, off offset:96
	v_lshlrev_b32_e32 v10, 16, v187
	v_mul_f32_e32 v9, v9, v10
	v_bfe_u32 v10, v9, 16, 1
	v_add3_u32 v9, v9, v10, s82
	global_store_short_d16_hi v[4:5], v9, off offset:128
	v_lshlrev_b32_e32 v9, 16, v188
	v_mul_f32_e32 v8, v8, v9
	v_bfe_u32 v9, v8, 16, 1
	v_add3_u32 v8, v8, v9, s82
	global_store_short_d16_hi v[4:5], v8, off offset:160
	v_lshlrev_b32_e32 v8, 16, v189
	v_mul_f32_e32 v6, v6, v8
	v_bfe_u32 v8, v6, 16, 1
	v_add3_u32 v6, v6, v8, s82
	global_store_short_d16_hi v[4:5], v6, off offset:192
	v_lshlrev_b32_e32 v0, 16, v190
	v_mul_f32_e32 v0, v2, v0
	v_bfe_u32 v1, v0, 16, 1
	v_add3_u32 v0, v0, v1, s82
	global_store_short_d16_hi v[4:5], v0, off offset:224
	v_add_f32_e32 v0, 0, v31
	v_add_f32_e32 v0, v0, v3
	v_add_f32_e32 v0, v0, v7
	v_add_f32_e32 v0, v0, v11
	v_add_f32_e32 v0, v0, v15
	v_add_f32_e32 v0, v0, v19
	v_mbcnt_lo_u32_b32 v1, s2, 0
	v_mbcnt_hi_u32_b32 v1, s2, v1
	v_add_f32_e32 v0, v0, v23
	v_lshlrev_b32_e32 v1, 2, v1
	v_add_f32_e32 v0, v0, v27
	v_xor_b32_e32 v2, 4, v1
	ds_bpermute_b32 v2, v2, v0
	s_mov_b32 s2, -1
	s_waitcnt lgkmcnt(0)
	v_add_f32_e32 v0, v0, v2
	v_xor_b32_e32 v2, 8, v1
	ds_bpermute_b32 v2, v2, v0
	s_waitcnt lgkmcnt(0)
	v_add_f32_e32 v0, v0, v2
	v_xor_b32_e32 v2, 16, v1
	ds_bpermute_b32 v2, v2, v0
	v_xor_b32_e32 v1, 32, v1
	s_waitcnt lgkmcnt(0)
	v_add_f32_e32 v0, v0, v2
	ds_bpermute_b32 v1, v1, v0
	s_waitcnt lgkmcnt(0)
	v_add_f32_e32 v0, v0, v1
	v_fmac_f32_e32 v3, 0xbc000000, v0
	v_fmac_f32_e32 v31, 0xbc000000, v0
	v_mul_f32_e32 v1, v3, v3
	v_fmac_f32_e32 v1, v31, v31
	v_fmac_f32_e32 v7, 0xbc000000, v0
	v_fmac_f32_e32 v1, v7, v7
	v_fmac_f32_e32 v11, 0xbc000000, v0
	v_fmac_f32_e32 v1, v11, v11
	v_fmac_f32_e32 v15, 0xbc000000, v0
	v_fmac_f32_e32 v1, v15, v15
	v_fmac_f32_e32 v19, 0xbc000000, v0
	v_fmac_f32_e32 v23, 0xbc000000, v0
	v_fmac_f32_e32 v27, 0xbc000000, v0
	v_mbcnt_lo_u32_b32 v0, s2, 0
	v_fmac_f32_e32 v1, v19, v19
	v_mbcnt_hi_u32_b32 v0, s2, v0
	v_fmac_f32_e32 v1, v23, v23
	v_lshlrev_b32_e32 v0, 2, v0
	v_fmac_f32_e32 v1, v27, v27
	v_xor_b32_e32 v2, 4, v0
	ds_bpermute_b32 v2, v2, v1
	s_waitcnt lgkmcnt(0)
; DEVFI float bf2f(bfraw h) { return __uint_as_float(((unsigned)h) << 16); }
; DEVFI bfraw f2bf(float x) { unsigned u = __float_as_uint(x); u += 0x7fffu + ((u >> 16) & 1u); return (bfraw)(u >> 16); }
; #define RG ((bfraw*)(kargs()->ws + O_RG))
; #define RO ((bfraw*)(kargs()->ws + O_RO))
; __global__ void __launch_bounds__(512) mega(Params p) {
;     ...
;           for (int j = 0; j < 4; ++j) { float s1 = 0;
; #pragma unroll
;             for (int ne = 0; ne < 8; ++ne) s1 += o[ne][j];
;             const float mean = red16(s1) * (1.f / 128.f); float s2 = 0;
; #pragma unroll
;             for (int ne = 0; ne < 8; ++ne) { const float dd = o[ne][j] - mean; s2 += dd * dd; }
;             const float rstd = 1.f / sqrtf(red16(s2) * (1.f / 128.f) + LN_EPS);
;             const long tok = tok0 + w * 16 + fq * 4 + j;
;             const bfraw* gp = RG + tok * 1024 + head * 128 + fr; bfraw* op = RO + tok * 1024 + head * 128 + fr;
; #pragma unroll
;             for (int ne = 0; ne < 8; ++ne) op[ne * 16] = f2bf((o[ne][j] - mean) * rstd * gw[ne] * bf2f(gp[ne * 16])); }
	v_add_f32_e32 v1, v1, v2
	v_xor_b32_e32 v2, 8, v0
	ds_bpermute_b32 v2, v2, v1
	s_waitcnt lgkmcnt(0)
	v_add_f32_e32 v1, v1, v2
	v_xor_b32_e32 v2, 16, v0
	ds_bpermute_b32 v2, v2, v1
	v_xor_b32_e32 v0, 32, v0
	s_waitcnt lgkmcnt(0)
	v_add_f32_e32 v1, v1, v2
	ds_bpermute_b32 v0, v0, v1
	s_waitcnt lgkmcnt(0)
	v_add_f32_e32 v0, v1, v0
	v_fmamk_f32 v0, v0, 0x3c000000, v183
	v_cmp_gt_f32_e32 vcc, s30, v0
	v_mul_f32_e32 v1, 0x4f800000, v0
	s_nop 0
	v_cndmask_b32_e32 v0, v0, v1, vcc
	v_sqrt_f32_e32 v1, v0
	s_nop 0
	v_add_u32_e32 v2, -1, v1
	v_fma_f32 v4, -v2, v1, v0
	v_cmp_ge_f32_e64 s[4:5], 0, v4
	v_add_u32_e32 v4, 1, v1
	s_nop 0
	v_cndmask_b32_e64 v2, v1, v2, s[4:5]
	v_fma_f32 v1, -v4, v1, v0
	v_cmp_lt_f32_e64 s[4:5], 0, v1
	s_nop 1
	v_cndmask_b32_e64 v1, v2, v4, s[4:5]
	v_mul_f32_e32 v2, 0x37800000, v1
	v_cndmask_b32_e32 v1, v1, v2, vcc
	v_cmp_class_f32_e32 vcc, v0, v222
	s_nop 1
	v_cndmask_b32_e32 v0, v1, v0, vcc
	s_mov_b64 s[2:3], s[0:1]
	s_load_dwordx2 s[2:3], s[2:3], 0xe8
	v_rcp_f32_e32 v2, v0
	s_nop 0
	v_fma_f32 v1, -v0, v2, 1.0
	v_fma_f32 v1, v1, v2, v2
	v_lshlrev_b64 v[4:5], 11, v[104:105]
	v_div_fixup_f32 v2, v1, v0, 1.0
	s_waitcnt lgkmcnt(0)
	v_lshl_add_u64 v[0:1], s[2:3], 0, v[4:5]
	v_lshl_add_u64 v[0:1], v[0:1], 0, s[12:13]
	v_lshl_add_u64 v[8:9], v[0:1], 0, v[176:177]
	v_lshl_add_u64 v[0:1], v[8:9], 0, s[42:43]
	v_add_co_u32_e32 v8, vcc, s68, v8
	s_mov_b64 s[2:3], s[0:1]
	s_nop 0
	v_addc_co_u32_e32 v9, vcc, 0, v9, vcc
	global_load_ushort v8, v[8:9], off
	global_load_ushort v184, v[0:1], off offset:32
	global_load_ushort v185, v[0:1], off offset:64
	global_load_ushort v186, v[0:1], off offset:96
	global_load_ushort v187, v[0:1], off offset:128
	global_load_ushort v188, v[0:1], off offset:160
	global_load_ushort v189, v[0:1], off offset:192
	global_load_ushort v190, v[0:1], off offset:224
	s_load_dwordx2 s[2:3], s[2:3], 0xe8
	v_mul_f32_e32 v6, v2, v31
	v_mul_f32_e32 v6, v6, v43
	v_mul_f32_e32 v3, v2, v3
	v_mul_f32_e32 v3, v3, v36
	s_waitcnt lgkmcnt(0)
	v_lshl_add_u64 v[4:5], s[2:3], 0, v[4:5]
	v_lshl_add_u64 v[4:5], v[4:5], 0, s[12:13]
	v_lshl_add_u64 v[12:13], v[4:5], 0, v[176:177]
	v_lshl_add_u64 v[4:5], v[12:13], 0, s[50:51]
	s_waitcnt vmcnt(0)
	v_lshlrev_b32_e32 v8, 16, v8
	v_mul_f32_e32 v6, v6, v8
	v_bfe_u32 v8, v6, 16, 1
	v_add3_u32 v6, v6, v8, s82
	v_add_co_u32_e32 v8, vcc, s69, v12
	s_nop 1
	v_addc_co_u32_e32 v9, vcc, 0, v13, vcc
	global_store_short_d16_hi v[8:9], v6, off
	v_lshlrev_b32_e32 v6, 16, v184
	v_mul_f32_e32 v3, v3, v6
	v_bfe_u32 v6, v3, 16, 1
	v_add3_u32 v3, v3, v6, s82
	global_store_short_d16_hi v[4:5], v3, off offset:32
	v_mul_f32_e32 v3, v2, v7
	v_mul_f32_e32 v3, v3, v37
	v_lshlrev_b32_e32 v6, 16, v185
	v_mul_f32_e32 v3, v3, v6
	v_bfe_u32 v6, v3, 16, 1
	v_add3_u32 v3, v3, v6, s82
	global_store_short_d16_hi v[4:5], v3, off offset:64
	v_mul_f32_e32 v3, v2, v11
	v_mul_f32_e32 v3, v3, v38
	v_lshlrev_b32_e32 v6, 16, v186
	v_mul_f32_e32 v3, v3, v6
	v_bfe_u32 v6, v3, 16, 1
	v_add3_u32 v3, v3, v6, s82
	global_store_short_d16_hi v[4:5], v3, off offset:96
	v_mul_f32_e32 v3, v2, v15
	v_mul_f32_e32 v3, v3, v39
	v_lshlrev_b32_e32 v6, 16, v187
	v_mul_f32_e32 v3, v3, v6
	v_bfe_u32 v6, v3, 16, 1
	v_add3_u32 v3, v3, v6, s82
	global_store_short_d16_hi v[4:5], v3, off offset:128
	v_mul_f32_e32 v3, v2, v19
	v_mul_f32_e32 v3, v3, v41
	v_lshlrev_b32_e32 v6, 16, v188
	v_mul_f32_e32 v3, v3, v6
	v_bfe_u32 v6, v3, 16, 1
	v_add3_u32 v3, v3, v6, s82
	global_store_short_d16_hi v[4:5], v3, off offset:160
	v_mul_f32_e32 v3, v2, v23
	v_mul_f32_e32 v3, v3, v40
	v_mul_f32_e32 v2, v2, v27
	v_mul_f32_e32 v2, v2, v42
	v_lshlrev_b32_e32 v6, 16, v189
	v_mul_f32_e32 v3, v3, v6
	v_bfe_u32 v6, v3, 16, 1
	v_add3_u32 v3, v3, v6, s82
	global_store_short_d16_hi v[4:5], v3, off offset:192
	v_lshlrev_b32_e32 v0, 16, v190
	v_mul_f32_e32 v0, v2, v0
	v_bfe_u32 v1, v0, 16, 1
	v_add3_u32 v0, v0, v1, s82
	global_store_short_d16_hi v[4:5], v0, off offset:224
	s_cbranch_scc0 .LBB0_2481
